# M1 RWKV pre-pass staging: row and mu loads of slice i+1 issued while slice i is processed
# baseline (speedup 1.0000x reference)
; #define LAS __attribute__((address_space(3)))
; __device__ __forceinline__ float bf2f(bf16_t h) { return __uint_as_float((unsigned)h << 16); }
; __device__ __forceinline__ bf16_t f2bf(float f) { return (bf16_t)(cvt_pk_bf16(f, 0.f) & 0xffffu); }
; __device__ __forceinline__ float sigmoidf(float x) { return rcpf(1.0f + __expf(-x)); }
; __device__ __forceinline__ void phase_m1(PP P, int l, LAS unsigned char* lds, const Ids I) {
;     ...
;             __syncthreads();
;             f32x4 aw[4], aa[4];
; #pragma unroll
;             for (int nt = 0; nt < 4; ++nt) { aw[nt] = (f32x4){0.f, 0.f, 0.f, 0.f}; aa[nt] = (f32x4){0.f, 0.f, 0.f, 0.f}; }
; #pragma unroll
;             for (int ks = 0; ks < 2; ++ks) { const bf16x8 fw = *(const LAS bf16x8*)(AL + l15 * 136 + ks * 32 + quad * 8), fa = *(const LAS bf16x8*)(AL + l15 * 136 + 64 + ks * 32 + quad * 8);
; #pragma unroll
;                 for (int nt = 0; nt < 4; ++nt) { aw[nt] = __builtin_amdgcn_mfma_f32_16x16x32_bf16(fw, bfw[nt][ks], aw[nt], 0, 0, 0); aa[nt] = __builtin_amdgcn_mfma_f32_16x16x32_bf16(fa, bfa[nt][ks], aa[nt], 0, 0, 0); } }
; #pragma unroll
;             for (int j = 0; j < 4; ++j) { const int tk = quad * 4 + j; const LAS bf16_t* xp = XSB + tk * 1536 + hd * 64 + l15; float xk[4], ar[4], kk[4]; float ssq = 0.f;
; #pragma unroll
;                 for (int nt = 0; nt < 4; ++nt) { xk[nt] = bf2f(xp[512 + nt * 16]); ar[nt] = sigmoidf(a0v[nt] + aa[nt][j]); kk[nt] = xk[nt] * kkv[nt]; ssq += kk[nt] * kk[nt]; }
;                 const float rn = 1.0f / fmaxf(sqrtf(row16_allsum(ssq)), 1e-12f);
; #pragma unroll
;                 for (int nt = 0; nt < 4; ++nt) { LAS bf16_t* ob = OR + tk * 512 + hd * 64 + nt * 16 + l15; const float kn = kk[nt] * rn;
;                     ob[0] = xp[nt * 16];
;                     ob[8192] = f2bf(0.60653066f * sigmoidf(w0v[nt] + aw[nt][j]));
;                     ob[2 * 8192] = f2bf(xk[nt] * (1.0f + (ar[nt] - 1.0f) * kav[nt]));
;                     ob[3 * 8192] = xp[1024 + nt * 16];
;                     ob[4 * 8192] = f2bf(kn); ob[5 * 8192] = f2bf(kn * ar[nt]); } }
.LBB0_226:
	s_or_b64 exec, exec, s[68:69]
	s_waitcnt vmcnt(0) lgkmcnt(0)
	s_barrier
	ds_read_b128 v[64:67], v196 offset:49152
	ds_read_b128 v[68:71], v196 offset:49280
	ds_read_b128 v[180:183], v196 offset:49216
	ds_read_b128 v[176:179], v196 offset:49344
	s_waitcnt lgkmcnt(2)
	v_mfma_f32_16x16x32_bf16 v[80:83], v[68:71], v[4:7], 0
	s_mov_b32 s3, 0xf800000
	v_readlane_b32 s6, v254, 37
	v_readlane_b32 s7, v254, 38
	v_mfma_f32_16x16x32_bf16 v[88:91], v[68:71], v[20:23], 0
	s_add_i32 s90, s90, s72
	v_add_u32_e32 v197, s2, v197
	v_add_u32_e32 v105, s2, v105
	s_waitcnt lgkmcnt(0)
	v_mfma_f32_16x16x32_bf16 v[92:95], v[176:179], v[12:15], v[80:83]
	v_add_u32_e32 v113, s2, v113
	v_add_u32_e32 v121, s2, v121
	v_add_u32_e32 v129, s2, v129
	v_mfma_f32_16x16x32_bf16 v[88:91], v[176:179], v[28:31], v[88:91]
	v_add_u32_e32 v137, s2, v137
	s_nop 2
	v_add_f32_e32 v92, v135, v92
	v_mul_f32_e32 v92, 0xbfb8aa3b, v92
	v_mfma_f32_16x16x32_bf16 v[72:75], v[64:67], v[0:3], 0
	v_exp_f32_e32 v92, v92
	v_add_f32_e32 v88, v143, v88
	v_mul_f32_e32 v88, 0xbfb8aa3b, v88
	v_mfma_f32_16x16x32_bf16 v[84:87], v[64:67], v[16:19], 0
	v_exp_f32_e32 v88, v88
	v_add_f32_e32 v92, 1.0, v92
	v_add_u32_e32 v153, s2, v153
	v_mfma_f32_16x16x32_bf16 v[246:249], v[68:71], v[36:39], 0
	v_add_f32_e32 v88, 1.0, v88
	s_cmpk_gt_i32 s90, 0x41f
	v_mfma_f32_16x16x32_bf16 v[76:79], v[180:183], v[8:11], v[72:75]
	v_mfma_f32_16x16x32_bf16 v[72:75], v[180:183], v[24:27], v[84:87]
	v_mfma_f32_16x16x32_bf16 v[84:87], v[176:179], v[44:47], v[246:249]
	s_nop 5
	v_add_f32_e32 v76, v103, v76
	v_mul_f32_e32 v76, 0xbfb8aa3b, v76
	v_exp_f32_e32 v76, v76
	v_mfma_f32_16x16x32_bf16 v[242:245], v[64:67], v[32:35], 0
	v_rcp_f32_e32 v246, v92
	s_waitcnt vmcnt(9)
	v_add_f32_e32 v84, v147, v84
	v_mul_f32_e32 v84, 0xbfb8aa3b, v84
	v_mfma_f32_16x16x32_bf16 v[250:253], v[68:71], v[52:55], 0
	ds_read_u16 v92, v239 offset:1056
	v_exp_f32_e32 v84, v84
	v_add_f32_e32 v76, 1.0, v76
	v_mfma_f32_16x16x32_bf16 v[68:71], v[180:183], v[40:43], v[242:245]
	v_rcp_f32_e32 v76, v76
	v_add_f32_e32 v84, 1.0, v84
	v_add_f32_e32 v72, v111, v72
	v_mfma_f32_16x16x32_bf16 v[80:83], v[176:179], v[60:63], v[250:253]
	ds_read_u16 v176, v239 offset:1024
	v_rcp_f32_e32 v242, v88
	ds_read_u16 v88, v239 offset:1088
	s_waitcnt lgkmcnt(2)
	v_lshlrev_b32_e32 v244, 16, v92
	s_waitcnt vmcnt(6)
	v_mul_f32_e32 v249, v189, v244
	s_waitcnt lgkmcnt(1)
	v_lshlrev_b32_e32 v248, 16, v176
	v_mul_f32_e32 v176, v188, v248
	s_waitcnt lgkmcnt(0)
	v_lshlrev_b32_e32 v92, 16, v88
	v_rcp_f32_e32 v88, v84
	ds_read_u16 v84, v239 offset:1120
	v_mul_f32_e32 v177, v249, v249
	v_fmac_f32_e32 v177, v176, v176
	s_waitcnt vmcnt(5)
	v_mul_f32_e32 v247, v190, v92
	v_fmac_f32_e32 v177, v247, v247
	s_waitcnt lgkmcnt(0)
	v_lshlrev_b32_e32 v84, 16, v84
	s_waitcnt vmcnt(4)
	v_mul_f32_e32 v243, v191, v84
	v_fmac_f32_e32 v177, v243, v243
	v_mfma_f32_16x16x32_bf16 v[64:67], v[64:67], v[48:51], 0
	v_mul_f32_e32 v76, 0x3f1b4598, v76
	v_add_f32_dpp v177, v177, v177 quad_perm:[1,0,3,2] row_mask:0xf bank_mask:0xf bound_ctrl:1
	v_cvt_pk_bf16_f32 v76, v76, v145
	v_mfma_f32_16x16x32_bf16 v[64:67], v[180:183], v[56:59], v[64:67]
	v_mul_f32_e32 v72, 0xbfb8aa3b, v72
	v_add_f32_dpp v177, v177, v177 quad_perm:[2,3,0,1] row_mask:0xf bank_mask:0xf bound_ctrl:1
	v_exp_f32_e32 v72, v72
	v_add_f32_e32 v68, v119, v68
	v_add_f32_dpp v177, v177, v177 row_half_mirror row_mask:0xf bank_mask:0xf bound_ctrl:1
	v_mul_f32_e32 v68, 0xbfb8aa3b, v68
	v_add_f32_e32 v72, 1.0, v72
	v_add_f32_dpp v177, v177, v177 row_mirror row_mask:0xf bank_mask:0xf bound_ctrl:1
	v_cmp_gt_f32_e32 vcc, s3, v177
	v_mul_f32_e32 v178, 0x4f800000, v177
	v_rcp_f32_e32 v72, v72
	v_cndmask_b32_e32 v177, v177, v178, vcc
	v_sqrt_f32_e32 v178, v177
	v_exp_f32_e32 v68, v68
	v_mul_f32_e32 v72, 0x3f1b4598, v72
	v_cvt_pk_bf16_f32 v72, v72, v145
	v_add_u32_e32 v179, -1, v178
	v_fma_f32 v180, -v179, v178, v177
	v_cmp_ge_f32_e64 s[50:51], 0, v180
	v_add_u32_e32 v180, 1, v178
	v_add_f32_e32 v68, 1.0, v68
	v_cndmask_b32_e64 v179, v178, v179, s[50:51]
	v_fma_f32 v178, -v180, v178, v177
	v_cmp_lt_f32_e64 s[50:51], 0, v178
	v_rcp_f32_e32 v68, v68
	v_add_f32_e32 v64, v127, v64
	v_cndmask_b32_e64 v178, v179, v180, s[50:51]
	v_mul_f32_e32 v179, 0x37800000, v178
	v_cndmask_b32_e32 v178, v178, v179, vcc
	v_cmp_class_f32_e32 vcc, v177, v175
	v_mul_f32_e32 v68, 0x3f1b4598, v68
	v_cvt_pk_bf16_f32 v68, v68, v145
	v_mul_f32_e32 v64, 0xbfb8aa3b, v64
	v_cndmask_b32_e32 v177, v178, v177, vcc
	v_max_f32_e32 v177, 0x2b8cbccc, v177
	v_div_scale_f32 v178, s[0:1], v177, v177, 1.0
	v_rcp_f32_e32 v179, v178
	v_add_f32_e32 v80, v187, v80
	v_exp_f32_e32 v64, v64
	v_mul_f32_e32 v80, 0xbfb8aa3b, v80
	v_fma_f32 v180, -v178, v179, 1.0
	v_fmac_f32_e32 v179, v180, v179
	v_div_scale_f32 v180, vcc, 1.0, v177, 1.0
	v_mul_f32_e32 v181, v180, v179
	v_fma_f32 v182, -v178, v181, v180
	v_fmac_f32_e32 v181, v182, v179
	v_fma_f32 v178, -v178, v181, v180
	v_div_fmas_f32 v178, v178, v179, v181
	v_div_fixup_f32 v245, v178, v177, 1.0
	ds_read_u16 v177, v239
	ds_write_b16 v198, v76 offset:16384
	v_add_f32_e32 v76, -1.0, v246
	s_waitcnt vmcnt(3)
	v_fma_f32 v76, v192, v76, 1.0
	v_mul_f32_e32 v76, v76, v248
	s_waitcnt lgkmcnt(1)
	ds_write_b16 v159, v177 offset:53504
	v_cvt_pk_bf16_f32 v76, v76, v145
	ds_write_b16 v198, v76 offset:32768
	ds_read_u16 v76, v239 offset:2048
	v_mul_f32_e32 v176, v176, v245
	v_add_u32_e32 v177, 0x1d100, v159
	v_exp_f32_e32 v80, v80
	v_add_f32_e32 v64, 1.0, v64
	s_waitcnt lgkmcnt(0)
	ds_write_b16 v198, v76 offset:49152
	v_cvt_pk_bf16_f32 v76, v176, v145
	ds_write_b16 v177, v76
	v_mul_f32_e32 v76, v246, v176
	v_add_u32_e32 v176, 0x21100, v159
	v_cvt_pk_bf16_f32 v76, v76, v145
	ds_write_b16 v176, v76
	ds_read_u16 v176, v239 offset:32
	ds_write_b16 v198, v72 offset:16416
	v_add_f32_e32 v72, -1.0, v242
	s_waitcnt vmcnt(2)
; #define LAS __attribute__((address_space(3)))
; __device__ __forceinline__ float bf2f(bf16_t h) { return __uint_as_float((unsigned)h << 16); }
; __device__ __forceinline__ bf16_t f2bf(float f) { return (bf16_t)(cvt_pk_bf16(f, 0.f) & 0xffffu); }
; __device__ __forceinline__ float sigmoidf(float x) { return rcpf(1.0f + __expf(-x)); }
; __device__ __forceinline__ void phase_m1(PP P, int l, LAS unsigned char* lds, const Ids I) {
;     ...
;             for (int j = 0; j < 4; ++j) { const int tk = quad * 4 + j; const LAS bf16_t* xp = XSB + tk * 1536 + hd * 64 + l15; float xk[4], ar[4], kk[4]; float ssq = 0.f;
; #pragma unroll
;                 for (int nt = 0; nt < 4; ++nt) { xk[nt] = bf2f(xp[512 + nt * 16]); ar[nt] = sigmoidf(a0v[nt] + aa[nt][j]); kk[nt] = xk[nt] * kkv[nt]; ssq += kk[nt] * kk[nt]; }
;                 const float rn = 1.0f / fmaxf(sqrtf(row16_allsum(ssq)), 1e-12f);
; #pragma unroll
;                 for (int nt = 0; nt < 4; ++nt) { LAS bf16_t* ob = OR + tk * 512 + hd * 64 + nt * 16 + l15; const float kn = kk[nt] * rn;
;                     ob[0] = xp[nt * 16];
;                     ob[8192] = f2bf(0.60653066f * sigmoidf(w0v[nt] + aw[nt][j]));
;                     ob[2 * 8192] = f2bf(xk[nt] * (1.0f + (ar[nt] - 1.0f) * kav[nt]));
;                     ob[3 * 8192] = xp[1024 + nt * 16];
;                     ob[4 * 8192] = f2bf(kn); ob[5 * 8192] = f2bf(kn * ar[nt]); } }
	v_fma_f32 v72, v193, v72, 1.0
	v_mul_f32_e32 v72, v72, v244
	s_waitcnt lgkmcnt(1)
	ds_write_b16 v159, v176 offset:53536
	v_cvt_pk_bf16_f32 v72, v72, v145
	ds_write_b16 v198, v72 offset:32800
	ds_read_u16 v72, v239 offset:2080
	v_mul_f32_e32 v76, v249, v245
	v_add_u32_e32 v176, 0x1d120, v159
	v_rcp_f32_e32 v64, v64
	v_add_f32_e32 v80, 1.0, v80
	s_waitcnt lgkmcnt(0)
	ds_write_b16 v198, v72 offset:49184
	v_cvt_pk_bf16_f32 v72, v76, v145
	ds_write_b16 v176, v72
	v_mul_f32_e32 v72, v242, v76
	v_add_u32_e32 v76, 0x21120, v159
	v_cvt_pk_bf16_f32 v72, v72, v145
	ds_write_b16 v76, v72
	ds_read_u16 v76, v239 offset:64
	ds_write_b16 v198, v68 offset:16448
	v_add_f32_e32 v68, -1.0, v88
	s_waitcnt vmcnt(1)
	v_fma_f32 v68, v194, v68, 1.0
	v_mul_f32_e32 v68, v68, v92
	s_waitcnt lgkmcnt(1)
	ds_write_b16 v159, v76 offset:53568
	v_cvt_pk_bf16_f32 v68, v68, v145
	ds_write_b16 v198, v68 offset:32832
	ds_read_u16 v68, v239 offset:2112
	v_mul_f32_e32 v72, v247, v245
	v_add_u32_e32 v76, 0x1d140, v159
	v_rcp_f32_e32 v80, v80
	v_mul_f32_e32 v64, 0x3f1b4598, v64
	s_waitcnt lgkmcnt(0)
	ds_write_b16 v198, v68 offset:49216
	v_cvt_pk_bf16_f32 v68, v72, v145
	ds_write_b16 v76, v68
	v_mul_f32_e32 v68, v88, v72
	v_cvt_pk_bf16_f32 v68, v68, v145
	ds_write_b16 v199, v68
	ds_read_u16 v72, v239 offset:96
	v_cvt_pk_bf16_f32 v64, v64, v145
	ds_write_b16 v198, v64 offset:16480
	v_add_f32_e32 v64, -1.0, v80
	s_waitcnt vmcnt(0)
	v_fma_f32 v64, v195, v64, 1.0
	v_mul_f32_e32 v64, v64, v84
	s_waitcnt lgkmcnt(1)
	ds_write_b16 v159, v72 offset:53600
	v_cvt_pk_bf16_f32 v64, v64, v145
	ds_write_b16 v198, v64 offset:32864
	ds_read_u16 v64, v239 offset:2144
	v_mul_f32_e32 v68, v243, v245
	v_add_f32_e32 v77, v103, v77
	v_mul_f32_e32 v77, 0xbfb8aa3b, v77
	v_exp_f32_e32 v77, v77
	s_waitcnt lgkmcnt(0)
	ds_write_b16 v198, v64 offset:49248
	v_cvt_pk_bf16_f32 v64, v68, v145
	ds_write_b16 v200, v64
	v_mul_f32_e32 v64, v80, v68
	v_cvt_pk_bf16_f32 v64, v64, v145
	ds_write_b16 v201, v64
	ds_read_u16 v64, v240 offset:1024
	v_add_f32_e32 v77, 1.0, v77
	v_rcp_f32_e32 v77, v77
	v_add_f32_e32 v73, v111, v73
	v_mul_f32_e32 v73, 0xbfb8aa3b, v73
	s_waitcnt lgkmcnt(0)
	v_lshlrev_b32_e32 v92, 16, v64
	v_add_f32_e32 v64, v135, v93
	v_mul_f32_e32 v64, 0xbfb8aa3b, v64
	v_exp_f32_e32 v64, v64
	v_mul_f32_e32 v93, v188, v92
	v_mul_f32_e32 v77, 0x3f1b4598, v77
	v_cvt_pk_bf16_f32 v77, v77, v145
	v_add_f32_e32 v64, 1.0, v64
	v_rcp_f32_e32 v88, v64
	ds_read_u16 v64, v240 offset:1056
	v_exp_f32_e32 v73, v73
	v_add_f32_e32 v69, v119, v69
	v_mul_f32_e32 v69, 0xbfb8aa3b, v69
	v_exp_f32_e32 v69, v69
	s_waitcnt lgkmcnt(0)
	v_lshlrev_b32_e32 v84, 16, v64
	v_add_f32_e32 v64, v143, v89
	v_mul_f32_e32 v64, 0xbfb8aa3b, v64
	v_exp_f32_e32 v64, v64
	v_mul_f32_e32 v176, v189, v84
	v_mul_f32_e32 v177, v176, v176
	v_fmac_f32_e32 v177, v93, v93
	v_add_f32_e32 v64, 1.0, v64
	v_rcp_f32_e32 v80, v64
	ds_read_u16 v64, v240 offset:1088
	v_add_f32_e32 v73, 1.0, v73
	v_rcp_f32_e32 v73, v73
	v_add_f32_e32 v69, 1.0, v69
	v_rcp_f32_e32 v69, v69
	s_waitcnt lgkmcnt(0)
	v_lshlrev_b32_e32 v76, 16, v64
	v_add_f32_e32 v64, v147, v85
	v_mul_f32_e32 v64, 0xbfb8aa3b, v64
	v_exp_f32_e32 v64, v64
	v_mul_f32_e32 v89, v190, v76
	v_fmac_f32_e32 v177, v89, v89
	v_mul_f32_e32 v73, 0x3f1b4598, v73
	v_add_f32_e32 v64, 1.0, v64
	v_rcp_f32_e32 v72, v64
	ds_read_u16 v64, v240 offset:1120
	v_cvt_pk_bf16_f32 v73, v73, v145
	v_mul_f32_e32 v69, 0x3f1b4598, v69
	v_cvt_pk_bf16_f32 v69, v69, v145
	v_add_f32_e32 v65, v127, v65
	s_waitcnt lgkmcnt(0)
	v_lshlrev_b32_e32 v68, 16, v64
	v_add_f32_e32 v64, v187, v81
	v_mul_f32_e32 v81, v191, v68
	v_fmac_f32_e32 v177, v81, v81
	v_mul_f32_e32 v65, 0xbfb8aa3b, v65
	v_exp_f32_e32 v65, v65
	v_add_f32_dpp v85, v177, v177 quad_perm:[1,0,3,2] row_mask:0xf bank_mask:0xf bound_ctrl:1
	v_mul_f32_e32 v64, 0xbfb8aa3b, v64
	v_exp_f32_e32 v64, v64
	v_add_f32_dpp v85, v85, v85 quad_perm:[2,3,0,1] row_mask:0xf bank_mask:0xf bound_ctrl:1
	v_add_f32_e32 v65, 1.0, v65
	v_rcp_f32_e32 v65, v65
	v_add_f32_dpp v85, v85, v85 row_half_mirror row_mask:0xf bank_mask:0xf bound_ctrl:1
	v_add_f32_e32 v64, 1.0, v64
	v_rcp_f32_e32 v64, v64
	v_add_f32_dpp v85, v85, v85 row_mirror row_mask:0xf bank_mask:0xf bound_ctrl:1
	v_cmp_gt_f32_e32 vcc, s3, v85
	v_mul_f32_e32 v177, 0x4f800000, v85
	v_mul_f32_e32 v65, 0x3f1b4598, v65
	v_cndmask_b32_e32 v85, v85, v177, vcc
	v_sqrt_f32_e32 v177, v85
	v_cvt_pk_bf16_f32 v65, v65, v145
	v_add_f32_e32 v78, v103, v78
	v_mul_f32_e32 v78, 0xbfb8aa3b, v78
	v_add_u32_e32 v178, -1, v177
	v_fma_f32 v179, -v178, v177, v85
	v_cmp_ge_f32_e64 s[50:51], 0, v179
	v_add_u32_e32 v179, 1, v177
	v_exp_f32_e32 v78, v78
	v_cndmask_b32_e64 v178, v177, v178, s[50:51]
	v_fma_f32 v177, -v179, v177, v85
	v_cmp_lt_f32_e64 s[50:51], 0, v177
	v_add_f32_e32 v78, 1.0, v78
	v_rcp_f32_e32 v78, v78
	v_cndmask_b32_e64 v177, v178, v179, s[50:51]
	v_mul_f32_e32 v178, 0x37800000, v177
	v_cndmask_b32_e32 v177, v177, v178, vcc
	v_cmp_class_f32_e32 vcc, v85, v175
	v_mul_f32_e32 v78, 0x3f1b4598, v78
	v_cvt_pk_bf16_f32 v78, v78, v145
	v_add_f32_e32 v74, v111, v74
	v_cndmask_b32_e32 v85, v177, v85, vcc
	v_max_f32_e32 v85, 0x2b8cbccc, v85
	v_div_scale_f32 v177, s[0:1], v85, v85, 1.0
	v_rcp_f32_e32 v178, v177
	v_mul_f32_e32 v74, 0xbfb8aa3b, v74
	v_exp_f32_e32 v74, v74
	v_add_f32_e32 v70, v119, v70
	v_fma_f32 v179, -v177, v178, 1.0
	v_fmac_f32_e32 v178, v179, v178
	v_div_scale_f32 v179, vcc, 1.0, v85, 1.0
	v_mul_f32_e32 v180, v179, v178
	v_fma_f32 v181, -v177, v180, v179
	v_fmac_f32_e32 v180, v181, v178
	v_fma_f32 v177, -v177, v180, v179
	v_div_fmas_f32 v177, v177, v178, v180
	v_div_fixup_f32 v85, v177, v85, 1.0
	ds_read_u16 v177, v240
	ds_write_b16 v203, v77 offset:16384
	v_add_f32_e32 v77, -1.0, v88
	v_fma_f32 v77, v192, v77, 1.0
	v_mul_f32_e32 v77, v77, v92
	s_waitcnt lgkmcnt(1)
; #define LAS __attribute__((address_space(3)))
; __device__ __forceinline__ float bf2f(bf16_t h) { return __uint_as_float((unsigned)h << 16); }
; __device__ __forceinline__ bf16_t f2bf(float f) { return (bf16_t)(cvt_pk_bf16(f, 0.f) & 0xffffu); }
; __device__ __forceinline__ float sigmoidf(float x) { return rcpf(1.0f + __expf(-x)); }
; __device__ __forceinline__ void phase_m1(PP P, int l, LAS unsigned char* lds, const Ids I) {
;     ...
;             for (int j = 0; j < 4; ++j) { const int tk = quad * 4 + j; const LAS bf16_t* xp = XSB + tk * 1536 + hd * 64 + l15; float xk[4], ar[4], kk[4]; float ssq = 0.f;
; #pragma unroll
;                 for (int nt = 0; nt < 4; ++nt) { xk[nt] = bf2f(xp[512 + nt * 16]); ar[nt] = sigmoidf(a0v[nt] + aa[nt][j]); kk[nt] = xk[nt] * kkv[nt]; ssq += kk[nt] * kk[nt]; }
;                 const float rn = 1.0f / fmaxf(sqrtf(row16_allsum(ssq)), 1e-12f);
; #pragma unroll
;                 for (int nt = 0; nt < 4; ++nt) { LAS bf16_t* ob = OR + tk * 512 + hd * 64 + nt * 16 + l15; const float kn = kk[nt] * rn;
;                     ob[0] = xp[nt * 16];
;                     ob[8192] = f2bf(0.60653066f * sigmoidf(w0v[nt] + aw[nt][j]));
;                     ob[2 * 8192] = f2bf(xk[nt] * (1.0f + (ar[nt] - 1.0f) * kav[nt]));
;                     ob[3 * 8192] = xp[1024 + nt * 16];
;                     ob[4 * 8192] = f2bf(kn); ob[5 * 8192] = f2bf(kn * ar[nt]); } }
	ds_write_b16 v202, v177 offset:53504
	v_cvt_pk_bf16_f32 v77, v77, v145
	ds_write_b16 v203, v77 offset:32768
	ds_read_u16 v77, v240 offset:2048
	v_mul_f32_e32 v93, v93, v85
	v_add_f32_e32 v74, 1.0, v74
	v_rcp_f32_e32 v74, v74
	v_mul_f32_e32 v70, 0xbfb8aa3b, v70
	s_waitcnt lgkmcnt(0)
	ds_write_b16 v203, v77 offset:49152
	v_cvt_pk_bf16_f32 v77, v93, v145
	ds_write_b16 v204, v77
	v_mul_f32_e32 v77, v88, v93
	v_cvt_pk_bf16_f32 v77, v77, v145
	ds_write_b16 v205, v77
	ds_read_u16 v88, v240 offset:32
	ds_write_b16 v203, v73 offset:16416
	v_add_f32_e32 v73, -1.0, v80
	v_fma_f32 v73, v193, v73, 1.0
	v_mul_f32_e32 v73, v73, v84
	s_waitcnt lgkmcnt(1)
	ds_write_b16 v202, v88 offset:53536
	v_cvt_pk_bf16_f32 v73, v73, v145
	ds_write_b16 v203, v73 offset:32800
	ds_read_u16 v73, v240 offset:2080
	v_mul_f32_e32 v77, v176, v85
	v_mul_f32_e32 v74, 0x3f1b4598, v74
	v_cvt_pk_bf16_f32 v74, v74, v145
	v_exp_f32_e32 v70, v70
	s_waitcnt lgkmcnt(0)
	ds_write_b16 v203, v73 offset:49184
	v_cvt_pk_bf16_f32 v73, v77, v145
	ds_write_b16 v206, v73
	v_mul_f32_e32 v73, v80, v77
	v_cvt_pk_bf16_f32 v73, v73, v145
	ds_write_b16 v207, v73
	ds_read_u16 v77, v240 offset:64
	ds_write_b16 v203, v69 offset:16448
	v_add_f32_e32 v69, -1.0, v72
	v_fma_f32 v69, v194, v69, 1.0
	v_mul_f32_e32 v69, v69, v76
	s_waitcnt lgkmcnt(1)
	ds_write_b16 v202, v77 offset:53568
	v_cvt_pk_bf16_f32 v69, v69, v145
	ds_write_b16 v203, v69 offset:32832
	ds_read_u16 v69, v240 offset:2112
	v_mul_f32_e32 v73, v89, v85
	v_add_f32_e32 v70, 1.0, v70
	v_rcp_f32_e32 v70, v70
	v_add_f32_e32 v66, v127, v66
	s_waitcnt lgkmcnt(0)
	ds_write_b16 v203, v69 offset:49216
	v_cvt_pk_bf16_f32 v69, v73, v145
	ds_write_b16 v208, v69
	v_mul_f32_e32 v69, v72, v73
	v_cvt_pk_bf16_f32 v69, v69, v145
	ds_write_b16 v209, v69
	ds_read_u16 v72, v240 offset:96
	ds_write_b16 v203, v65 offset:16480
	v_add_f32_e32 v65, -1.0, v64
	v_fma_f32 v65, v195, v65, 1.0
	v_mul_f32_e32 v65, v65, v68
	s_waitcnt lgkmcnt(1)
	ds_write_b16 v202, v72 offset:53600
	v_cvt_pk_bf16_f32 v65, v65, v145
	ds_write_b16 v203, v65 offset:32864
	ds_read_u16 v65, v240 offset:2144
	v_mul_f32_e32 v69, v81, v85
	v_mul_f32_e32 v64, v64, v69
	v_cvt_pk_bf16_f32 v64, v64, v145
	ds_write_b16 v211, v64
	s_waitcnt lgkmcnt(1)
	ds_write_b16 v203, v65 offset:49248
	v_cvt_pk_bf16_f32 v65, v69, v145
	ds_write_b16 v210, v65
	ds_read_u16 v64, v240 offset:4096
	v_mul_f32_e32 v70, 0x3f1b4598, v70
	v_cvt_pk_bf16_f32 v70, v70, v145
	v_mul_f32_e32 v66, 0xbfb8aa3b, v66
	v_exp_f32_e32 v66, v66
	s_waitcnt lgkmcnt(0)
	v_lshlrev_b32_e32 v84, 16, v64
	v_add_f32_e32 v64, v135, v94
	v_mul_f32_e32 v64, 0xbfb8aa3b, v64
	v_exp_f32_e32 v64, v64
	v_mul_f32_e32 v85, v188, v84
	v_add_f32_e32 v66, 1.0, v66
	v_rcp_f32_e32 v66, v66
	v_add_f32_e32 v64, 1.0, v64
	v_rcp_f32_e32 v80, v64
	ds_read_u16 v64, v240 offset:4128
	v_mul_f32_e32 v66, 0x3f1b4598, v66
	v_cvt_pk_bf16_f32 v66, v66, v145
	v_add_f32_e32 v79, v103, v79
	v_mul_f32_e32 v79, 0xbfb8aa3b, v79
	s_waitcnt lgkmcnt(0)
	v_lshlrev_b32_e32 v76, 16, v64
	v_add_f32_e32 v64, v143, v90
	v_mul_f32_e32 v64, 0xbfb8aa3b, v64
	v_exp_f32_e32 v64, v64
	v_mul_f32_e32 v88, v189, v76
	v_mul_f32_e32 v77, v88, v88
	v_fmac_f32_e32 v77, v85, v85
	v_add_f32_e32 v64, 1.0, v64
	v_rcp_f32_e32 v72, v64
	ds_read_u16 v64, v240 offset:4160
	v_exp_f32_e32 v79, v79
	v_add_f32_e32 v75, v111, v75
	v_mul_f32_e32 v75, 0xbfb8aa3b, v75
	v_exp_f32_e32 v75, v75
	s_waitcnt lgkmcnt(0)
	v_lshlrev_b32_e32 v69, 16, v64
	v_add_f32_e32 v64, v147, v86
	v_mul_f32_e32 v64, 0xbfb8aa3b, v64
	v_exp_f32_e32 v64, v64
	v_mul_f32_e32 v81, v190, v69
	v_fmac_f32_e32 v77, v81, v81
	v_add_f32_e32 v79, 1.0, v79
	v_add_f32_e32 v64, 1.0, v64
	v_rcp_f32_e32 v68, v64
	ds_read_u16 v64, v240 offset:4192
	v_rcp_f32_e32 v79, v79
	v_add_f32_e32 v75, 1.0, v75
	v_rcp_f32_e32 v75, v75
	v_add_f32_e32 v71, v119, v71
	s_waitcnt lgkmcnt(0)
	v_lshlrev_b32_e32 v65, 16, v64
	v_mul_f32_e32 v73, v191, v65
	v_fmac_f32_e32 v77, v73, v73
	v_add_f32_e32 v64, v187, v82
	v_mul_f32_e32 v64, 0xbfb8aa3b, v64
	v_add_f32_dpp v77, v77, v77 quad_perm:[1,0,3,2] row_mask:0xf bank_mask:0xf bound_ctrl:1
	v_exp_f32_e32 v64, v64
	v_mul_f32_e32 v79, 0x3f1b4598, v79
	v_add_f32_dpp v77, v77, v77 quad_perm:[2,3,0,1] row_mask:0xf bank_mask:0xf bound_ctrl:1
	v_cvt_pk_bf16_f32 v79, v79, v145
	v_add_f32_e32 v64, 1.0, v64
	v_rcp_f32_e32 v64, v64
	v_add_f32_dpp v77, v77, v77 row_half_mirror row_mask:0xf bank_mask:0xf bound_ctrl:1
	v_mul_f32_e32 v75, 0x3f1b4598, v75
	v_cvt_pk_bf16_f32 v75, v75, v145
	v_mul_f32_e32 v71, 0xbfb8aa3b, v71
	v_add_f32_dpp v77, v77, v77 row_mirror row_mask:0xf bank_mask:0xf bound_ctrl:1
	v_cmp_gt_f32_e32 vcc, s3, v77
	v_mul_f32_e32 v82, 0x4f800000, v77
	v_exp_f32_e32 v71, v71
	v_cndmask_b32_e32 v77, v77, v82, vcc
	v_sqrt_f32_e32 v82, v77
	v_add_f32_e32 v67, v127, v67
	v_add_f32_e32 v71, 1.0, v71
	v_rcp_f32_e32 v71, v71
	v_add_u32_e32 v86, -1, v82
	v_fma_f32 v89, -v86, v82, v77
	v_cmp_ge_f32_e64 s[50:51], 0, v89
	v_add_u32_e32 v89, 1, v82
	v_mul_f32_e32 v71, 0x3f1b4598, v71
	v_cndmask_b32_e64 v86, v82, v86, s[50:51]
	v_fma_f32 v82, -v89, v82, v77
	v_cmp_lt_f32_e64 s[50:51], 0, v82
	v_cvt_pk_bf16_f32 v71, v71, v145
	v_mul_f32_e32 v67, 0xbfb8aa3b, v67
	v_exp_f32_e32 v67, v67
	v_cndmask_b32_e64 v82, v86, v89, s[50:51]
	v_mul_f32_e32 v86, 0x37800000, v82
	v_cndmask_b32_e32 v82, v82, v86, vcc
	v_cmp_class_f32_e32 vcc, v77, v175
	v_add_f32_e32 v67, 1.0, v67
	v_rcp_f32_e32 v67, v67
	v_cndmask_b32_e32 v77, v82, v77, vcc
	v_max_f32_e32 v77, 0x2b8cbccc, v77
	v_div_scale_f32 v82, s[0:1], v77, v77, 1.0
	v_rcp_f32_e32 v86, v82
	v_mul_f32_e32 v67, 0x3f1b4598, v67
	v_cvt_pk_bf16_f32 v67, v67, v145
	v_fma_f32 v89, -v82, v86, 1.0
	v_fmac_f32_e32 v86, v89, v86
	v_div_scale_f32 v89, vcc, 1.0, v77, 1.0
	v_mul_f32_e32 v90, v89, v86
	v_fma_f32 v92, -v82, v90, v89
	v_fmac_f32_e32 v90, v92, v86
	v_fma_f32 v82, -v82, v90, v89
	v_div_fmas_f32 v82, v82, v86, v90
	v_div_fixup_f32 v77, v82, v77, 1.0
	v_mul_f32_e32 v82, v85, v77
	ds_read_u16 v85, v240 offset:3072
	ds_write_b16 v213, v78 offset:16384
	v_add_f32_e32 v78, -1.0, v80
	v_fma_f32 v78, v192, v78, 1.0
	v_mul_f32_e32 v78, v78, v84
	s_waitcnt lgkmcnt(1)
; #define LAS __attribute__((address_space(3)))
; __device__ __forceinline__ float bf2f(bf16_t h) { return __uint_as_float((unsigned)h << 16); }
; __device__ __forceinline__ bf16_t f2bf(float f) { return (bf16_t)(cvt_pk_bf16(f, 0.f) & 0xffffu); }
; __device__ __forceinline__ float sigmoidf(float x) { return rcpf(1.0f + __expf(-x)); }
; __device__ __forceinline__ void phase_m1(PP P, int l, LAS unsigned char* lds, const Ids I) {
;     ...
;             for (int j = 0; j < 4; ++j) { const int tk = quad * 4 + j; const LAS bf16_t* xp = XSB + tk * 1536 + hd * 64 + l15; float xk[4], ar[4], kk[4]; float ssq = 0.f;
; #pragma unroll
;                 for (int nt = 0; nt < 4; ++nt) { xk[nt] = bf2f(xp[512 + nt * 16]); ar[nt] = sigmoidf(a0v[nt] + aa[nt][j]); kk[nt] = xk[nt] * kkv[nt]; ssq += kk[nt] * kk[nt]; }
;                 const float rn = 1.0f / fmaxf(sqrtf(row16_allsum(ssq)), 1e-12f);
; #pragma unroll
;                 for (int nt = 0; nt < 4; ++nt) { LAS bf16_t* ob = OR + tk * 512 + hd * 64 + nt * 16 + l15; const float kn = kk[nt] * rn;
;                     ob[0] = xp[nt * 16];
;                     ob[8192] = f2bf(0.60653066f * sigmoidf(w0v[nt] + aw[nt][j]));
;                     ob[2 * 8192] = f2bf(xk[nt] * (1.0f + (ar[nt] - 1.0f) * kav[nt]));
;                     ob[3 * 8192] = xp[1024 + nt * 16];
;                     ob[4 * 8192] = f2bf(kn); ob[5 * 8192] = f2bf(kn * ar[nt]); } }
;             __syncthreads();
	ds_write_b16 v212, v85 offset:53504
	v_cvt_pk_bf16_f32 v78, v78, v145
	ds_write_b16 v213, v78 offset:32768
	ds_read_u16 v78, v240 offset:5120
	s_waitcnt lgkmcnt(0)
	ds_write_b16 v213, v78 offset:49152
	v_cvt_pk_bf16_f32 v78, v82, v145
	ds_write_b16 v214, v78
	v_mul_f32_e32 v78, v80, v82
	v_cvt_pk_bf16_f32 v78, v78, v145
	ds_write_b16 v215, v78
	ds_read_u16 v80, v240 offset:3104
	ds_write_b16 v213, v74 offset:16416
	v_add_f32_e32 v74, -1.0, v72
	v_fma_f32 v74, v193, v74, 1.0
	v_mul_f32_e32 v74, v74, v76
	s_waitcnt lgkmcnt(1)
	ds_write_b16 v212, v80 offset:53536
	v_cvt_pk_bf16_f32 v74, v74, v145
	ds_write_b16 v213, v74 offset:32800
	ds_read_u16 v74, v240 offset:5152
	v_mul_f32_e32 v78, v88, v77
	v_mul_f32_e32 v72, v72, v78
	v_cvt_pk_bf16_f32 v72, v72, v145
	ds_write_b16 v217, v72
	s_waitcnt lgkmcnt(1)
	ds_write_b16 v213, v74 offset:49184
	v_cvt_pk_bf16_f32 v74, v78, v145
	ds_write_b16 v216, v74
	ds_read_u16 v74, v240 offset:3136
	ds_write_b16 v213, v70 offset:16448
	v_add_f32_e32 v70, -1.0, v68
	v_fma_f32 v70, v194, v70, 1.0
	v_mul_f32_e32 v69, v70, v69
	s_waitcnt lgkmcnt(1)
	ds_write_b16 v212, v74 offset:53568
	v_cvt_pk_bf16_f32 v69, v69, v145
	ds_write_b16 v213, v69 offset:32832
	ds_read_u16 v69, v240 offset:5184
	v_mul_f32_e32 v72, v81, v77
	v_mul_f32_e32 v68, v68, v72
	v_cvt_pk_bf16_f32 v68, v68, v145
	ds_write_b16 v219, v68
	s_waitcnt lgkmcnt(1)
	ds_write_b16 v213, v69 offset:49216
	v_cvt_pk_bf16_f32 v69, v72, v145
	ds_write_b16 v218, v69
	ds_read_u16 v69, v240 offset:3168
	ds_write_b16 v213, v66 offset:16480
	v_add_f32_e32 v66, -1.0, v64
	v_fma_f32 v66, v195, v66, 1.0
	v_mul_f32_e32 v65, v66, v65
	s_waitcnt lgkmcnt(1)
	ds_write_b16 v212, v69 offset:53600
	v_cvt_pk_bf16_f32 v65, v65, v145
	ds_write_b16 v213, v65 offset:32864
	ds_read_u16 v65, v240 offset:5216
	v_mul_f32_e32 v68, v73, v77
	v_mul_f32_e32 v64, v64, v68
	v_cvt_pk_bf16_f32 v64, v64, v145
	ds_write_b16 v221, v64
	s_waitcnt lgkmcnt(1)
	ds_write_b16 v213, v65 offset:49248
	v_cvt_pk_bf16_f32 v65, v68, v145
	ds_write_b16 v220, v65
	ds_read_u16 v64, v240 offset:7168
	s_waitcnt lgkmcnt(0)
	v_lshlrev_b32_e32 v77, 16, v64
	v_add_f32_e32 v64, v135, v95
	v_mul_f32_e32 v64, 0xbfb8aa3b, v64
	v_exp_f32_e32 v64, v64
	v_mul_f32_e32 v78, v188, v77
	v_add_f32_e32 v64, 1.0, v64
	v_rcp_f32_e32 v74, v64
	ds_read_u16 v64, v240 offset:7200
	s_waitcnt lgkmcnt(0)
	v_lshlrev_b32_e32 v72, 16, v64
	v_add_f32_e32 v64, v143, v91
	v_mul_f32_e32 v64, 0xbfb8aa3b, v64
	v_exp_f32_e32 v64, v64
	v_mul_f32_e32 v80, v189, v72
	v_mul_f32_e32 v73, v80, v80
	v_fmac_f32_e32 v73, v78, v78
	v_add_f32_e32 v64, 1.0, v64
	v_rcp_f32_e32 v69, v64
	ds_read_u16 v64, v240 offset:7232
	s_waitcnt lgkmcnt(0)
	v_lshlrev_b32_e32 v68, 16, v64
	v_add_f32_e32 v64, v147, v87
	v_mul_f32_e32 v64, 0xbfb8aa3b, v64
	v_exp_f32_e32 v64, v64
	v_mul_f32_e32 v76, v190, v68
	v_fmac_f32_e32 v73, v76, v76
	v_add_f32_e32 v64, 1.0, v64
	v_rcp_f32_e32 v66, v64
	ds_read_u16 v64, v240 offset:7264
	s_waitcnt lgkmcnt(0)
	v_lshlrev_b32_e32 v65, 16, v64
	v_mul_f32_e32 v70, v191, v65
	v_fmac_f32_e32 v73, v70, v70
	v_add_f32_e32 v64, v187, v83
	v_mul_f32_e32 v64, 0xbfb8aa3b, v64
	v_add_f32_dpp v73, v73, v73 quad_perm:[1,0,3,2] row_mask:0xf bank_mask:0xf bound_ctrl:1
	v_exp_f32_e32 v64, v64
	s_nop 0
	v_add_f32_dpp v73, v73, v73 quad_perm:[2,3,0,1] row_mask:0xf bank_mask:0xf bound_ctrl:1
	v_add_f32_e32 v64, 1.0, v64
	s_nop 0
	v_add_f32_dpp v73, v73, v73 row_half_mirror row_mask:0xf bank_mask:0xf bound_ctrl:1
	v_rcp_f32_e32 v64, v64
	s_nop 0
	v_add_f32_dpp v73, v73, v73 row_mirror row_mask:0xf bank_mask:0xf bound_ctrl:1
	v_cmp_gt_f32_e32 vcc, s3, v73
	v_mul_f32_e32 v81, 0x4f800000, v73
	s_nop 0
	v_cndmask_b32_e32 v73, v73, v81, vcc
	v_sqrt_f32_e32 v81, v73
	s_nop 0
	v_add_u32_e32 v82, -1, v81
	v_fma_f32 v83, -v82, v81, v73
	v_cmp_ge_f32_e64 s[50:51], 0, v83
	v_add_u32_e32 v83, 1, v81
	s_nop 0
	v_cndmask_b32_e64 v82, v81, v82, s[50:51]
	v_fma_f32 v81, -v83, v81, v73
	v_cmp_lt_f32_e64 s[50:51], 0, v81
	s_nop 1
	v_cndmask_b32_e64 v81, v82, v83, s[50:51]
	v_mul_f32_e32 v82, 0x37800000, v81
	v_cndmask_b32_e32 v81, v81, v82, vcc
	v_cmp_class_f32_e32 vcc, v73, v175
	v_readlane_b32 s50, v254, 39
	v_readlane_b32 s51, v254, 40
	v_cndmask_b32_e32 v73, v81, v73, vcc
	v_max_f32_e32 v73, 0x2b8cbccc, v73
	v_div_scale_f32 v81, s[0:1], v73, v73, 1.0
	v_rcp_f32_e32 v82, v81
	v_readlane_b32 s0, v254, 35
	v_readlane_b32 s1, v254, 36
	v_fma_f32 v83, -v81, v82, 1.0
	v_fmac_f32_e32 v82, v83, v82
	v_div_scale_f32 v83, vcc, 1.0, v73, 1.0
	v_mul_f32_e32 v84, v83, v82
	v_fma_f32 v85, -v81, v84, v83
	v_fmac_f32_e32 v84, v85, v82
	v_fma_f32 v81, -v81, v84, v83
	v_div_fmas_f32 v81, v81, v82, v84
	v_div_fixup_f32 v73, v81, v73, 1.0
	ds_read_u16 v81, v240 offset:6144
	ds_write_b16 v223, v79 offset:16384
	v_add_f32_e32 v79, -1.0, v74
	v_fma_f32 v79, v192, v79, 1.0
	v_mul_f32_e32 v77, v79, v77
	s_waitcnt lgkmcnt(1)
	ds_write_b16 v222, v81 offset:53504
	v_cvt_pk_bf16_f32 v77, v77, v145
	ds_write_b16 v223, v77 offset:32768
	ds_read_u16 v77, v240 offset:8192
	v_mul_f32_e32 v78, v78, v73
	v_mul_f32_e32 v74, v74, v78
	v_cvt_pk_bf16_f32 v74, v74, v145
	ds_write_b16 v225, v74
	s_waitcnt lgkmcnt(1)
	ds_write_b16 v223, v77 offset:49152
	v_cvt_pk_bf16_f32 v77, v78, v145
	ds_write_b16 v224, v77
	ds_read_u16 v77, v240 offset:6176
	ds_write_b16 v223, v75 offset:16416
	v_add_f32_e32 v75, -1.0, v69
	v_fma_f32 v75, v193, v75, 1.0
	v_mul_f32_e32 v72, v75, v72
	s_waitcnt lgkmcnt(1)
	ds_write_b16 v222, v77 offset:53536
	v_cvt_pk_bf16_f32 v72, v72, v145
	ds_write_b16 v223, v72 offset:32800
	ds_read_u16 v72, v240 offset:8224
	v_mul_f32_e32 v74, v80, v73
	v_mul_f32_e32 v69, v69, v74
	v_cvt_pk_bf16_f32 v69, v69, v145
	ds_write_b16 v227, v69
	s_waitcnt lgkmcnt(1)
	ds_write_b16 v223, v72 offset:49184
	v_cvt_pk_bf16_f32 v72, v74, v145
	ds_write_b16 v226, v72
	ds_read_u16 v72, v240 offset:6208
	ds_write_b16 v223, v71 offset:16448
	v_add_f32_e32 v71, -1.0, v66
	v_fma_f32 v71, v194, v71, 1.0
	v_mul_f32_e32 v68, v71, v68
	s_waitcnt lgkmcnt(1)
	ds_write_b16 v222, v72 offset:53568
	v_cvt_pk_bf16_f32 v68, v68, v145
	ds_write_b16 v223, v68 offset:32832
	ds_read_u16 v68, v240 offset:8256
	v_mul_f32_e32 v69, v76, v73
	v_mul_f32_e32 v66, v66, v69
	v_cvt_pk_bf16_f32 v66, v66, v145
	ds_write_b16 v229, v66
	s_waitcnt lgkmcnt(1)
	ds_write_b16 v223, v68 offset:49216
	v_cvt_pk_bf16_f32 v68, v69, v145
	ds_write_b16 v228, v68
	ds_read_u16 v68, v240 offset:6240
	ds_write_b16 v223, v67 offset:16480
	v_add_f32_e32 v67, -1.0, v64
	v_fma_f32 v67, v195, v67, 1.0
	v_mul_f32_e32 v65, v67, v65
	s_waitcnt lgkmcnt(1)
	ds_write_b16 v222, v68 offset:53600
	v_cvt_pk_bf16_f32 v65, v65, v145
	ds_write_b16 v223, v65 offset:32864
	ds_read_u16 v65, v240 offset:8288
	v_mul_f32_e32 v66, v70, v73
	v_mul_f32_e32 v64, v64, v66
	v_cvt_pk_bf16_f32 v64, v64, v145
	ds_write_b16 v231, v64
	s_waitcnt lgkmcnt(1)
	ds_write_b16 v223, v65 offset:49248
	v_cvt_pk_bf16_f32 v65, v66, v145
	ds_write_b16 v230, v65
	s_waitcnt lgkmcnt(0)
	s_barrier
; #define LAS __attribute__((address_space(3)))
; __device__ __forceinline__ void phase_m1(PP P, int l, LAS unsigned char* lds, const Ids I) {
;     ...
;             for (int it = 0; it < 7; ++it) { const int e = tid + 512 * it;
;                 if (e < 16 * 208) { const int tok = e / 208, col = (e - tok * 208) * 8, r = r0 + tok, t = t_in_seq(r);
;                     float cf[8], pf[8]; unpack8(*(const u32x4*)(PR + (size_t)r * INW + 1024 + col), cf);
;                     if (t > 0) unpack8(*(const u32x4*)(PR + (size_t)(r - 1) * INW + 1024 + col), pf);
;                     else if (r < MTP) {
; #pragma unroll
;                         for (int j = 0; j < 8; ++j) pf[j] = 0.f; }
;                     else { const float* sp = P->in[I_SSHIFT] + ((size_t)l * 128 + ((r - MTP) >> 2)) * PW + col; const f32x4 s0 = *(const f32x4*)sp, s1 = *(const f32x4*)(sp + 4);
; #pragma unroll
;                         for (int j = 0; j < 4; ++j) { pf[j] = s0[j]; pf[4 + j] = s1[j]; } }
;     ...
;             for (int i = 0; i < 2; ++i) { const int idx = tid + 512 * i, tok = idx >> 6, c8 = (idx & 63) * 8; const size_t o = (size_t)(r0 + tok) * 512 + c8; const LAS bf16_t* ob = OR + tok * 512 + c8;
;                 *(u32x4*)(arr + A_R * AS + o) = *(const LAS u32x4*)(ob); *(u32x4*)(arr + A_EW * AS + o) = *(const LAS u32x4*)(ob + 8192); *(u32x4*)(arr + A_KF * AS + o) = *(const LAS u32x4*)(ob + 2 * 8192);
;                 *(u32x4*)(arr + A_V * AS + o) = *(const LAS u32x4*)(ob + 3 * 8192); *(u32x4*)(arr + A_KK * AS + o) = *(const LAS u32x4*)(ob + 4 * 8192); *(u32x4*)(arr + A_BB * AS + o) = *(const LAS u32x4*)(ob + 5 * 8192); }
	v_add_u32_e32 v68, s54, v97
	ds_read_b128 v[64:67], v232
	v_ashrrev_i32_e32 v69, 31, v68
	v_lshlrev_b64 v[68:69], 10, v[68:69]
	v_or_b32_e32 v68, v68, v241
	v_lshl_add_u64 v[70:71], s[0:1], 0, v[68:69]
	s_waitcnt lgkmcnt(0)
	global_store_dwordx4 v[70:71], v[64:67], off
	ds_read_b128 v[64:67], v232 offset:16384
	v_lshl_add_u64 v[70:71], s[74:75], 0, v[68:69]
	v_add_u32_e32 v97, s2, v97
	s_waitcnt lgkmcnt(0)
	global_store_dwordx4 v[70:71], v[64:67], off
	ds_read_b128 v[64:67], v232 offset:32768
	v_lshl_add_u64 v[70:71], s[6:7], 0, v[68:69]
	s_waitcnt lgkmcnt(0)
	global_store_dwordx4 v[70:71], v[64:67], off
	ds_read_b128 v[64:67], v232 offset:49152
	v_lshl_add_u64 v[70:71], s[50:51], 0, v[68:69]
	s_waitcnt lgkmcnt(0)
	global_store_dwordx4 v[70:71], v[64:67], off
	ds_read_b128 v[64:67], v233
	v_lshl_add_u64 v[70:71], s[52:53], 0, v[68:69]
	v_lshl_add_u64 v[68:69], s[70:71], 0, v[68:69]
	s_waitcnt lgkmcnt(0)
	global_store_dwordx4 v[70:71], v[64:67], off
	ds_read_b128 v[64:67], v234
	s_waitcnt lgkmcnt(0)
	global_store_dwordx4 v[68:69], v[64:67], off
	v_add_u32_e32 v68, s54, v235
	ds_read_b128 v[64:67], v236
	v_ashrrev_i32_e32 v69, 31, v68
	v_lshlrev_b64 v[68:69], 10, v[68:69]
	v_or_b32_e32 v68, v68, v241
	v_lshl_add_u64 v[70:71], s[0:1], 0, v[68:69]
	s_waitcnt lgkmcnt(0)
	global_store_dwordx4 v[70:71], v[64:67], off
	ds_read_b128 v[64:67], v236 offset:16384
	v_lshl_add_u64 v[70:71], s[74:75], 0, v[68:69]
	v_add_u32_e32 v235, s2, v235
	s_waitcnt lgkmcnt(0)
	global_store_dwordx4 v[70:71], v[64:67], off
	ds_read_b128 v[64:67], v236 offset:32768
	v_lshl_add_u64 v[70:71], s[6:7], 0, v[68:69]
	s_waitcnt lgkmcnt(0)
	global_store_dwordx4 v[70:71], v[64:67], off
	ds_read_b128 v[64:67], v236 offset:49152
	v_lshl_add_u64 v[70:71], s[50:51], 0, v[68:69]
	s_waitcnt lgkmcnt(0)
	global_store_dwordx4 v[70:71], v[64:67], off
	ds_read_b128 v[64:67], v237
	v_lshl_add_u64 v[70:71], s[52:53], 0, v[68:69]
	v_lshl_add_u64 v[68:69], s[70:71], 0, v[68:69]
	s_waitcnt lgkmcnt(0)
	global_store_dwordx4 v[70:71], v[64:67], off
	ds_read_b128 v[64:67], v238
	s_waitcnt lgkmcnt(0)
	global_store_dwordx4 v[68:69], v[64:67], off
	s_cbranch_scc1 .LBB0_318
.LBB0_227:
	v_add_u32_e32 v252, s54, v197
	v_mad_i64_i32 v[250:251], s[0:1], v252, s73, v[160:161]
	global_load_dwordx4 v[242:245], v[250:251], off offset:2048
	v_add_u32_e32 v252, -1, v252
	v_mad_i64_i32 v[250:251], s[0:1], v252, s73, v[160:161]
	global_load_dwordx4 v[246:249], v[250:251], off offset:2048
	global_load_dwordx4 v[180:183], v[100:101], off offset:16
	global_load_dwordx4 v[176:179], v[100:101], off
	s_and_saveexec_b64 s[68:69], s[4:5]
	s_cbranch_execz .LBB0_240
	v_add_u32_e32 v76, s54, v197
	s_waitcnt vmcnt(0)
	v_mov_b32_e32 v72, v242
	v_mov_b32_e32 v73, v243
	v_mov_b32_e32 v74, v244
	v_mov_b32_e32 v75, v245
	v_mov_b32_e32 v64, v246
	v_mov_b32_e32 v65, v247
	v_mov_b32_e32 v66, v248
	v_mov_b32_e32 v67, v249
	v_add_u32_e32 v252, s54, v105
	v_mad_i64_i32 v[250:251], s[0:1], v252, s73, v[162:163]
	global_load_dwordx4 v[242:245], v[250:251], off offset:2048
	v_add_u32_e32 v252, -1, v252
	v_mad_i64_i32 v[250:251], s[0:1], v252, s73, v[162:163]
	global_load_dwordx4 v[246:249], v[250:251], off offset:2048
	v_cmp_gt_i32_e64 s[50:51], s91, v76
	v_cmp_lt_i32_e32 vcc, s76, v76
	s_nop 0
	v_cndmask_b32_e64 v252, 3, v185, s[50:51]
	v_and_b32_e32 v252, v252, v76
	v_cmp_ne_u32_e64 s[50:51], 0, v252
	s_and_saveexec_b64 s[0:1], s[50:51]
	s_xor_b64 s[6:7], exec, s[0:1]
	s_cbranch_execz .LBB0_230
	v_lshlrev_b32_e32 v68, 16, v64
	v_and_b32_e32 v69, 0xffff0000, v64
	v_lshlrev_b32_e32 v70, 16, v65
	v_and_b32_e32 v71, 0xffff0000, v65
	v_lshlrev_b32_e32 v64, 16, v66
	v_and_b32_e32 v65, 0xffff0000, v66
	v_lshlrev_b32_e32 v66, 16, v67
	v_and_b32_e32 v67, 0xffff0000, v67
.LBB0_230:
	s_andn2_saveexec_b64 s[50:51], s[6:7]
	s_cbranch_execz .LBB0_234
	v_mov_b32_e32 v67, 0
	v_mov_b32_e32 v66, 0
	v_mov_b32_e32 v65, 0
	v_mov_b32_e32 v64, 0
	v_mov_b32_e32 v71, 0
	v_mov_b32_e32 v70, 0
	v_mov_b32_e32 v69, 0
	v_mov_b32_e32 v68, 0
	s_and_saveexec_b64 s[6:7], vcc
	s_cbranch_execz .LBB0_233
	s_load_dwordx2 s[0:1], s[88:89], 0x30
	v_add_u32_e32 v64, 0xffffc000, v76
	v_lshrrev_b32_e32 v64, 2, v64
	v_readlane_b32 s3, v254, 46
	s_nop 1
	v_add_u32_e32 v66, s3, v64
	s_waitcnt lgkmcnt(0)
	v_mov_b64_e32 v[64:65], s[0:1]
	s_movk_i32 s0, 0x1c00
	v_mad_u64_u32 v[64:65], s[0:1], v66, s0, v[64:65]
	v_lshl_add_u64 v[64:65], v[98:99], 2, v[64:65]
	global_load_dwordx4 v[68:71], v[64:65], off
	s_nop 0
	global_load_dwordx4 v[64:67], v[64:65], off offset:16
	s_waitcnt vmcnt(0)

; __device__ __forceinline__ float tanh_f(float x) { return 1.0f - 2.0f * rcpf(1.0f + __expf(2.0f * x)); }
; __device__ __forceinline__ void phase_m1(PP P, int l, LAS unsigned char* lds, const Ids I) {
;     ...
;                     const f32x4 m0 = *(const f32x4*)(mu + col), m1 = *(const f32x4*)(mu + col + 4); float xs[8];
; #pragma unroll
;                     for (int j = 0; j < 4; ++j) { xs[j] = cf[j] + (pf[j] - cf[j]) * m0[j]; xs[4 + j] = cf[4 + j] + (pf[4 + j] - cf[4 + j]) * m1[j]; }
;                     if (col >= 1536 && col < 1600) {
; #pragma unroll
;                         for (int j = 0; j < 8; ++j) xs[j] = tanh_f(xs[j]); }
.LBB0_234:
	s_or_b64 exec, exec, s[50:51]
	v_lshlrev_b32_e32 v86, 16, v74
	v_and_b32_e32 v87, 0xffff0000, v74
	v_lshlrev_b32_e32 v88, 16, v75
	v_and_b32_e32 v89, 0xffff0000, v75
	v_lshlrev_b32_e32 v82, 16, v72
	v_and_b32_e32 v83, 0xffff0000, v72
	v_lshlrev_b32_e32 v84, 16, v73
	v_and_b32_e32 v85, 0xffff0000, v73
	v_pk_add_f32 v[68:69], v[68:69], v[82:83] neg_lo:[0,1] neg_hi:[0,1]
	v_pk_add_f32 v[64:65], v[64:65], v[86:87] neg_lo:[0,1] neg_hi:[0,1]
	v_pk_fma_f32 v[72:73], v[176:177], v[68:69], v[82:83]
	v_pk_fma_f32 v[68:69], v[64:65], v[180:181], v[86:87]
	v_pk_add_f32 v[64:65], v[70:71], v[84:85] neg_lo:[0,1] neg_hi:[0,1]
	s_nop 0
	v_pk_fma_f32 v[74:75], v[178:179], v[64:65], v[84:85]
	v_pk_add_f32 v[64:65], v[66:67], v[88:89] neg_lo:[0,1] neg_hi:[0,1]
	s_nop 0
	v_pk_fma_f32 v[70:71], v[64:65], v[182:183], v[88:89]
	global_load_dwordx4 v[180:183], v[108:109], off offset:16
	global_load_dwordx4 v[176:179], v[108:109], off
	s_mov_b64 s[50:51], exec
	v_readlane_b32 s0, v254, 55
	v_readlane_b32 s1, v254, 56
	s_and_b64 s[0:1], s[50:51], s[0:1]
	s_mov_b64 exec, s[0:1]
	s_cbranch_execz .LBB0_236
	v_add_f32_e32 v64, v72, v72
	v_add_f32_e32 v65, v73, v73
	v_add_f32_e32 v66, v74, v74
	v_add_f32_e32 v67, v75, v75
	v_add_f32_e32 v68, v68, v68
	v_add_f32_e32 v69, v69, v69
	v_add_f32_e32 v70, v70, v70
	v_add_f32_e32 v71, v71, v71
	v_mul_f32_e32 v64, 0x3fb8aa3b, v64
	v_mul_f32_e32 v65, 0x3fb8aa3b, v65
	v_mul_f32_e32 v66, 0x3fb8aa3b, v66
	v_mul_f32_e32 v67, 0x3fb8aa3b, v67
	v_mul_f32_e32 v68, 0x3fb8aa3b, v68
	v_mul_f32_e32 v69, 0x3fb8aa3b, v69
	v_mul_f32_e32 v70, 0x3fb8aa3b, v70
	v_mul_f32_e32 v71, 0x3fb8aa3b, v71
	v_exp_f32_e32 v64, v64
	v_exp_f32_e32 v65, v65
	v_exp_f32_e32 v66, v66
	v_exp_f32_e32 v67, v67
	v_exp_f32_e32 v68, v68
	v_exp_f32_e32 v69, v69
	v_exp_f32_e32 v70, v70
	v_exp_f32_e32 v71, v71
	v_add_f32_e32 v64, 1.0, v64
	v_add_f32_e32 v65, 1.0, v65
	v_add_f32_e32 v66, 1.0, v66
	v_add_f32_e32 v67, 1.0, v67
	v_add_f32_e32 v68, 1.0, v68
	v_add_f32_e32 v69, 1.0, v69
	v_add_f32_e32 v70, 1.0, v70
	v_add_f32_e32 v71, 1.0, v71
	v_rcp_f32_e32 v64, v64
	v_rcp_f32_e32 v66, v66
	v_rcp_f32_e32 v68, v68
	v_rcp_f32_e32 v70, v70
	v_rcp_f32_e32 v71, v71
	v_rcp_f32_e32 v69, v69
	v_rcp_f32_e32 v67, v67
	v_rcp_f32_e32 v65, v65
	v_pk_fma_f32 v[70:71], v[70:71], -2.0, 1.0 op_sel_hi:[1,0,0]
	v_pk_fma_f32 v[68:69], v[68:69], -2.0, 1.0 op_sel_hi:[1,0,0]
	v_pk_fma_f32 v[74:75], v[66:67], -2.0, 1.0 op_sel_hi:[1,0,0]
	v_pk_fma_f32 v[72:73], v[64:65], -2.0, 1.0 op_sel_hi:[1,0,0]

; __device__ __forceinline__ void phase_m1(PP P, int l, LAS unsigned char* lds, const Ids I) {
;     ...
;             for (int it = 0; it < 7; ++it) { const int e = tid + 512 * it;
;                 if (e < 16 * 208) { const int tok = e / 208, col = (e - tok * 208) * 8, r = r0 + tok, t = t_in_seq(r);
;                     float cf[8], pf[8]; unpack8(*(const u32x4*)(PR + (size_t)r * INW + 1024 + col), cf);
;                     if (t > 0) unpack8(*(const u32x4*)(PR + (size_t)(r - 1) * INW + 1024 + col), pf);
;                     else if (r < MTP) {
; #pragma unroll
;                         for (int j = 0; j < 8; ++j) pf[j] = 0.f; }
;                     else { const float* sp = P->in[I_SSHIFT] + ((size_t)l * 128 + ((r - MTP) >> 2)) * PW + col; const f32x4 s0 = *(const f32x4*)sp, s1 = *(const f32x4*)(sp + 4);
; #pragma unroll
;                         for (int j = 0; j < 4; ++j) { pf[j] = s0[j]; pf[4 + j] = s1[j]; } }
.LBB0_240:
	s_or_b64 exec, exec, s[68:69]
	s_and_saveexec_b64 s[68:69], s[10:11]
	s_cbranch_execz .LBB0_253
	v_add_u32_e32 v76, s54, v105
	s_waitcnt vmcnt(0)
	v_mov_b32_e32 v72, v242
	v_mov_b32_e32 v73, v243
	v_mov_b32_e32 v74, v244
	v_mov_b32_e32 v75, v245
	v_mov_b32_e32 v64, v246
	v_mov_b32_e32 v65, v247
	v_mov_b32_e32 v66, v248
	v_mov_b32_e32 v67, v249
	v_add_u32_e32 v252, s54, v113
	v_mad_i64_i32 v[250:251], s[0:1], v252, s73, v[164:165]
	global_load_dwordx4 v[242:245], v[250:251], off offset:2048
	v_add_u32_e32 v252, -1, v252
	v_mad_i64_i32 v[250:251], s[0:1], v252, s73, v[164:165]
	global_load_dwordx4 v[246:249], v[250:251], off offset:2048
	v_cmp_gt_i32_e64 s[50:51], s91, v76
	v_cmp_lt_i32_e32 vcc, s76, v76
	s_nop 0
	v_cndmask_b32_e64 v252, 3, v185, s[50:51]
	v_and_b32_e32 v252, v252, v76
	v_cmp_ne_u32_e64 s[50:51], 0, v252
	s_and_saveexec_b64 s[0:1], s[50:51]
	s_xor_b64 s[6:7], exec, s[0:1]
	s_cbranch_execz .LBB0_243
	v_lshlrev_b32_e32 v68, 16, v64
	v_and_b32_e32 v69, 0xffff0000, v64
	v_lshlrev_b32_e32 v70, 16, v65
	v_and_b32_e32 v71, 0xffff0000, v65
	v_lshlrev_b32_e32 v64, 16, v66
	v_and_b32_e32 v65, 0xffff0000, v66
	v_lshlrev_b32_e32 v66, 16, v67
	v_and_b32_e32 v67, 0xffff0000, v67
.LBB0_243:
	s_andn2_saveexec_b64 s[50:51], s[6:7]
	s_cbranch_execz .LBB0_247
	v_mov_b32_e32 v67, 0
	v_mov_b32_e32 v66, 0
	v_mov_b32_e32 v65, 0
	v_mov_b32_e32 v64, 0
	v_mov_b32_e32 v71, 0
	v_mov_b32_e32 v70, 0
	v_mov_b32_e32 v69, 0
	v_mov_b32_e32 v68, 0
	s_and_saveexec_b64 s[6:7], vcc
	s_cbranch_execz .LBB0_246
	s_load_dwordx2 s[0:1], s[88:89], 0x30
	v_add_u32_e32 v64, 0xffffc000, v76
	v_lshrrev_b32_e32 v64, 2, v64
	v_readlane_b32 s3, v254, 46
	s_nop 1
	v_add_u32_e32 v66, s3, v64
	s_waitcnt lgkmcnt(0)
	v_mov_b64_e32 v[64:65], s[0:1]
	s_movk_i32 s0, 0x1c00
	v_mad_u64_u32 v[64:65], s[0:1], v66, s0, v[64:65]
	v_lshl_add_u64 v[64:65], v[106:107], 2, v[64:65]
	global_load_dwordx4 v[68:71], v[64:65], off
	s_nop 0
	global_load_dwordx4 v[64:67], v[64:65], off offset:16
	s_waitcnt vmcnt(0)

; __device__ __forceinline__ float tanh_f(float x) { return 1.0f - 2.0f * rcpf(1.0f + __expf(2.0f * x)); }
; __device__ __forceinline__ void phase_m1(PP P, int l, LAS unsigned char* lds, const Ids I) {
;     ...
;                     const f32x4 m0 = *(const f32x4*)(mu + col), m1 = *(const f32x4*)(mu + col + 4); float xs[8];
; #pragma unroll
;                     for (int j = 0; j < 4; ++j) { xs[j] = cf[j] + (pf[j] - cf[j]) * m0[j]; xs[4 + j] = cf[4 + j] + (pf[4 + j] - cf[4 + j]) * m1[j]; }
;                     if (col >= 1536 && col < 1600) {
; #pragma unroll
;                         for (int j = 0; j < 8; ++j) xs[j] = tanh_f(xs[j]); }
.LBB0_247:
	s_or_b64 exec, exec, s[50:51]
	v_lshlrev_b32_e32 v86, 16, v74
	v_and_b32_e32 v87, 0xffff0000, v74
	v_lshlrev_b32_e32 v88, 16, v75
	v_and_b32_e32 v89, 0xffff0000, v75
	v_lshlrev_b32_e32 v82, 16, v72
	v_and_b32_e32 v83, 0xffff0000, v72
	v_lshlrev_b32_e32 v84, 16, v73
	v_and_b32_e32 v85, 0xffff0000, v73
	v_pk_add_f32 v[68:69], v[68:69], v[82:83] neg_lo:[0,1] neg_hi:[0,1]
	v_pk_add_f32 v[64:65], v[64:65], v[86:87] neg_lo:[0,1] neg_hi:[0,1]
	v_pk_fma_f32 v[72:73], v[176:177], v[68:69], v[82:83]
	v_pk_fma_f32 v[68:69], v[64:65], v[180:181], v[86:87]
	v_pk_add_f32 v[64:65], v[70:71], v[84:85] neg_lo:[0,1] neg_hi:[0,1]
	s_nop 0
	v_pk_fma_f32 v[74:75], v[178:179], v[64:65], v[84:85]
	v_pk_add_f32 v[64:65], v[66:67], v[88:89] neg_lo:[0,1] neg_hi:[0,1]
	s_nop 0
	v_pk_fma_f32 v[70:71], v[64:65], v[182:183], v[88:89]
	global_load_dwordx4 v[180:183], v[116:117], off offset:16
	global_load_dwordx4 v[176:179], v[116:117], off
	s_mov_b64 s[50:51], exec
	v_readlane_b32 s0, v254, 59
	v_readlane_b32 s1, v254, 60
	s_and_b64 s[0:1], s[50:51], s[0:1]
	s_mov_b64 exec, s[0:1]
	s_cbranch_execz .LBB0_249
	v_add_f32_e32 v64, v72, v72
	v_add_f32_e32 v65, v73, v73
	v_add_f32_e32 v66, v74, v74
	v_add_f32_e32 v67, v75, v75
	v_add_f32_e32 v68, v68, v68
	v_add_f32_e32 v69, v69, v69
	v_add_f32_e32 v70, v70, v70
	v_add_f32_e32 v71, v71, v71
	v_mul_f32_e32 v64, 0x3fb8aa3b, v64
	v_mul_f32_e32 v65, 0x3fb8aa3b, v65
	v_mul_f32_e32 v66, 0x3fb8aa3b, v66
	v_mul_f32_e32 v67, 0x3fb8aa3b, v67
	v_mul_f32_e32 v68, 0x3fb8aa3b, v68
	v_mul_f32_e32 v69, 0x3fb8aa3b, v69
	v_mul_f32_e32 v70, 0x3fb8aa3b, v70
	v_mul_f32_e32 v71, 0x3fb8aa3b, v71
	v_exp_f32_e32 v64, v64
	v_exp_f32_e32 v65, v65
	v_exp_f32_e32 v66, v66
	v_exp_f32_e32 v67, v67
	v_exp_f32_e32 v68, v68
	v_exp_f32_e32 v69, v69
	v_exp_f32_e32 v70, v70
	v_exp_f32_e32 v71, v71
	v_add_f32_e32 v64, 1.0, v64
	v_add_f32_e32 v65, 1.0, v65
	v_add_f32_e32 v66, 1.0, v66
	v_add_f32_e32 v67, 1.0, v67
	v_add_f32_e32 v68, 1.0, v68
	v_add_f32_e32 v69, 1.0, v69
	v_add_f32_e32 v70, 1.0, v70
	v_add_f32_e32 v71, 1.0, v71
	v_rcp_f32_e32 v64, v64
	v_rcp_f32_e32 v66, v66
	v_rcp_f32_e32 v68, v68
	v_rcp_f32_e32 v70, v70
	v_rcp_f32_e32 v71, v71
	v_rcp_f32_e32 v69, v69
	v_rcp_f32_e32 v67, v67
	v_rcp_f32_e32 v65, v65
	v_pk_fma_f32 v[70:71], v[70:71], -2.0, 1.0 op_sel_hi:[1,0,0]
	v_pk_fma_f32 v[68:69], v[68:69], -2.0, 1.0 op_sel_hi:[1,0,0]
	v_pk_fma_f32 v[74:75], v[66:67], -2.0, 1.0 op_sel_hi:[1,0,0]
	v_pk_fma_f32 v[72:73], v[64:65], -2.0, 1.0 op_sel_hi:[1,0,0]

; __device__ __forceinline__ void phase_m1(PP P, int l, LAS unsigned char* lds, const Ids I) {
;     ...
;             for (int it = 0; it < 7; ++it) { const int e = tid + 512 * it;
;                 if (e < 16 * 208) { const int tok = e / 208, col = (e - tok * 208) * 8, r = r0 + tok, t = t_in_seq(r);
;                     float cf[8], pf[8]; unpack8(*(const u32x4*)(PR + (size_t)r * INW + 1024 + col), cf);
;                     if (t > 0) unpack8(*(const u32x4*)(PR + (size_t)(r - 1) * INW + 1024 + col), pf);
;                     else if (r < MTP) {
; #pragma unroll
;                         for (int j = 0; j < 8; ++j) pf[j] = 0.f; }
;                     else { const float* sp = P->in[I_SSHIFT] + ((size_t)l * 128 + ((r - MTP) >> 2)) * PW + col; const f32x4 s0 = *(const f32x4*)sp, s1 = *(const f32x4*)(sp + 4);
; #pragma unroll
;                         for (int j = 0; j < 4; ++j) { pf[j] = s0[j]; pf[4 + j] = s1[j]; } }
.LBB0_253:
	s_or_b64 exec, exec, s[68:69]
	s_and_saveexec_b64 s[68:69], s[16:17]
	s_cbranch_execz .LBB0_266
	v_add_u32_e32 v76, s54, v113
	s_waitcnt vmcnt(0)
	v_mov_b32_e32 v72, v242
	v_mov_b32_e32 v73, v243
	v_mov_b32_e32 v74, v244
	v_mov_b32_e32 v75, v245
	v_mov_b32_e32 v64, v246
	v_mov_b32_e32 v65, v247
	v_mov_b32_e32 v66, v248
	v_mov_b32_e32 v67, v249
	v_add_u32_e32 v252, s54, v121
	v_mad_i64_i32 v[250:251], s[0:1], v252, s73, v[166:167]
	global_load_dwordx4 v[242:245], v[250:251], off offset:2048
	v_add_u32_e32 v252, -1, v252
	v_mad_i64_i32 v[250:251], s[0:1], v252, s73, v[166:167]
	global_load_dwordx4 v[246:249], v[250:251], off offset:2048
	v_cmp_gt_i32_e64 s[50:51], s91, v76
	v_cmp_lt_i32_e32 vcc, s76, v76
	s_nop 0
	v_cndmask_b32_e64 v252, 3, v185, s[50:51]
	v_and_b32_e32 v252, v252, v76
	v_cmp_ne_u32_e64 s[50:51], 0, v252
	s_and_saveexec_b64 s[0:1], s[50:51]
	s_xor_b64 s[6:7], exec, s[0:1]
	s_cbranch_execz .LBB0_256
	v_lshlrev_b32_e32 v68, 16, v64
	v_and_b32_e32 v69, 0xffff0000, v64
	v_lshlrev_b32_e32 v70, 16, v65
	v_and_b32_e32 v71, 0xffff0000, v65
	v_lshlrev_b32_e32 v64, 16, v66
	v_and_b32_e32 v65, 0xffff0000, v66
	v_lshlrev_b32_e32 v66, 16, v67
	v_and_b32_e32 v67, 0xffff0000, v67
.LBB0_256:
	s_andn2_saveexec_b64 s[50:51], s[6:7]
	s_cbranch_execz .LBB0_260
	v_mov_b32_e32 v67, 0
	v_mov_b32_e32 v66, 0
	v_mov_b32_e32 v65, 0
	v_mov_b32_e32 v64, 0
	v_mov_b32_e32 v71, 0
	v_mov_b32_e32 v70, 0
	v_mov_b32_e32 v69, 0
	v_mov_b32_e32 v68, 0
	s_and_saveexec_b64 s[6:7], vcc
	s_cbranch_execz .LBB0_259
	s_load_dwordx2 s[0:1], s[88:89], 0x30
	v_add_u32_e32 v64, 0xffffc000, v76
	v_lshrrev_b32_e32 v64, 2, v64
	v_readlane_b32 s3, v254, 46
	s_nop 1
	v_add_u32_e32 v66, s3, v64
	s_waitcnt lgkmcnt(0)
	v_mov_b64_e32 v[64:65], s[0:1]
	s_movk_i32 s0, 0x1c00
	v_mad_u64_u32 v[64:65], s[0:1], v66, s0, v[64:65]
	v_lshl_add_u64 v[64:65], v[114:115], 2, v[64:65]
	global_load_dwordx4 v[68:71], v[64:65], off
	s_nop 0
	global_load_dwordx4 v[64:67], v[64:65], off offset:16
	s_waitcnt vmcnt(0)

; __device__ __forceinline__ float tanh_f(float x) { return 1.0f - 2.0f * rcpf(1.0f + __expf(2.0f * x)); }
; __device__ __forceinline__ void phase_m1(PP P, int l, LAS unsigned char* lds, const Ids I) {
;     ...
;                     const f32x4 m0 = *(const f32x4*)(mu + col), m1 = *(const f32x4*)(mu + col + 4); float xs[8];
; #pragma unroll
;                     for (int j = 0; j < 4; ++j) { xs[j] = cf[j] + (pf[j] - cf[j]) * m0[j]; xs[4 + j] = cf[4 + j] + (pf[4 + j] - cf[4 + j]) * m1[j]; }
;                     if (col >= 1536 && col < 1600) {
; #pragma unroll
;                         for (int j = 0; j < 8; ++j) xs[j] = tanh_f(xs[j]); }
.LBB0_260:
	s_or_b64 exec, exec, s[50:51]
	v_lshlrev_b32_e32 v86, 16, v74
	v_and_b32_e32 v87, 0xffff0000, v74
	v_lshlrev_b32_e32 v88, 16, v75
	v_and_b32_e32 v89, 0xffff0000, v75
	v_lshlrev_b32_e32 v82, 16, v72
	v_and_b32_e32 v83, 0xffff0000, v72
	v_lshlrev_b32_e32 v84, 16, v73
	v_and_b32_e32 v85, 0xffff0000, v73
	v_pk_add_f32 v[68:69], v[68:69], v[82:83] neg_lo:[0,1] neg_hi:[0,1]
	v_pk_add_f32 v[64:65], v[64:65], v[86:87] neg_lo:[0,1] neg_hi:[0,1]
	v_pk_fma_f32 v[72:73], v[176:177], v[68:69], v[82:83]
	v_pk_fma_f32 v[68:69], v[64:65], v[180:181], v[86:87]
	v_pk_add_f32 v[64:65], v[70:71], v[84:85] neg_lo:[0,1] neg_hi:[0,1]
	s_nop 0
	v_pk_fma_f32 v[74:75], v[178:179], v[64:65], v[84:85]
	v_pk_add_f32 v[64:65], v[66:67], v[88:89] neg_lo:[0,1] neg_hi:[0,1]
	s_nop 0
	v_pk_fma_f32 v[70:71], v[64:65], v[182:183], v[88:89]
	global_load_dwordx4 v[180:183], v[124:125], off offset:16
	global_load_dwordx4 v[176:179], v[124:125], off
	s_and_saveexec_b64 s[50:51], s[18:19]
	s_cbranch_execz .LBB0_262
	v_add_f32_e32 v64, v72, v72
	v_add_f32_e32 v65, v73, v73
	v_add_f32_e32 v66, v74, v74
	v_add_f32_e32 v67, v75, v75
	v_add_f32_e32 v68, v68, v68
	v_add_f32_e32 v69, v69, v69
	v_add_f32_e32 v70, v70, v70
	v_add_f32_e32 v71, v71, v71
	v_mul_f32_e32 v64, 0x3fb8aa3b, v64
	v_mul_f32_e32 v65, 0x3fb8aa3b, v65
	v_mul_f32_e32 v66, 0x3fb8aa3b, v66
	v_mul_f32_e32 v67, 0x3fb8aa3b, v67
	v_mul_f32_e32 v68, 0x3fb8aa3b, v68
	v_mul_f32_e32 v69, 0x3fb8aa3b, v69
	v_mul_f32_e32 v70, 0x3fb8aa3b, v70
	v_mul_f32_e32 v71, 0x3fb8aa3b, v71
	v_exp_f32_e32 v64, v64
	v_exp_f32_e32 v65, v65
	v_exp_f32_e32 v66, v66
	v_exp_f32_e32 v67, v67
	v_exp_f32_e32 v68, v68
	v_exp_f32_e32 v69, v69
	v_exp_f32_e32 v70, v70
	v_exp_f32_e32 v71, v71
	v_add_f32_e32 v64, 1.0, v64
	v_add_f32_e32 v65, 1.0, v65
	v_add_f32_e32 v66, 1.0, v66
	v_add_f32_e32 v67, 1.0, v67
	v_add_f32_e32 v68, 1.0, v68
	v_add_f32_e32 v69, 1.0, v69
	v_add_f32_e32 v70, 1.0, v70
	v_add_f32_e32 v71, 1.0, v71
	v_rcp_f32_e32 v64, v64
	v_rcp_f32_e32 v66, v66
	v_rcp_f32_e32 v68, v68
	v_rcp_f32_e32 v70, v70
	v_rcp_f32_e32 v71, v71
	v_rcp_f32_e32 v69, v69
	v_rcp_f32_e32 v67, v67
	v_rcp_f32_e32 v65, v65
	v_pk_fma_f32 v[70:71], v[70:71], -2.0, 1.0 op_sel_hi:[1,0,0]
	v_pk_fma_f32 v[68:69], v[68:69], -2.0, 1.0 op_sel_hi:[1,0,0]
	v_pk_fma_f32 v[74:75], v[66:67], -2.0, 1.0 op_sel_hi:[1,0,0]
	v_pk_fma_f32 v[72:73], v[64:65], -2.0, 1.0 op_sel_hi:[1,0,0]

; __device__ __forceinline__ void phase_m1(PP P, int l, LAS unsigned char* lds, const Ids I) {
;     ...
;             for (int it = 0; it < 7; ++it) { const int e = tid + 512 * it;
;                 if (e < 16 * 208) { const int tok = e / 208, col = (e - tok * 208) * 8, r = r0 + tok, t = t_in_seq(r);
;                     float cf[8], pf[8]; unpack8(*(const u32x4*)(PR + (size_t)r * INW + 1024 + col), cf);
;                     if (t > 0) unpack8(*(const u32x4*)(PR + (size_t)(r - 1) * INW + 1024 + col), pf);
;                     else if (r < MTP) {
; #pragma unroll
;                         for (int j = 0; j < 8; ++j) pf[j] = 0.f; }
;                     else { const float* sp = P->in[I_SSHIFT] + ((size_t)l * 128 + ((r - MTP) >> 2)) * PW + col; const f32x4 s0 = *(const f32x4*)sp, s1 = *(const f32x4*)(sp + 4);
; #pragma unroll
;                         for (int j = 0; j < 4; ++j) { pf[j] = s0[j]; pf[4 + j] = s1[j]; } }
.LBB0_266:
	s_or_b64 exec, exec, s[68:69]
	s_and_saveexec_b64 s[68:69], s[22:23]
	s_cbranch_execz .LBB0_279
	v_add_u32_e32 v76, s54, v121
	s_waitcnt vmcnt(0)
	v_mov_b32_e32 v72, v242
	v_mov_b32_e32 v73, v243
	v_mov_b32_e32 v74, v244
	v_mov_b32_e32 v75, v245
	v_mov_b32_e32 v64, v246
	v_mov_b32_e32 v65, v247
	v_mov_b32_e32 v66, v248
	v_mov_b32_e32 v67, v249
	v_add_u32_e32 v252, s54, v129
	v_mad_i64_i32 v[250:251], s[0:1], v252, s73, v[168:169]
	global_load_dwordx4 v[242:245], v[250:251], off offset:2048
	v_add_u32_e32 v252, -1, v252
	v_mad_i64_i32 v[250:251], s[0:1], v252, s73, v[168:169]
	global_load_dwordx4 v[246:249], v[250:251], off offset:2048
	v_cmp_gt_i32_e64 s[50:51], s91, v76
	v_cmp_lt_i32_e32 vcc, s76, v76
	s_nop 0
	v_cndmask_b32_e64 v252, 3, v185, s[50:51]
	v_and_b32_e32 v252, v252, v76
	v_cmp_ne_u32_e64 s[50:51], 0, v252
	s_and_saveexec_b64 s[0:1], s[50:51]
	s_xor_b64 s[6:7], exec, s[0:1]
	s_cbranch_execz .LBB0_269
	v_lshlrev_b32_e32 v68, 16, v64
	v_and_b32_e32 v69, 0xffff0000, v64
	v_lshlrev_b32_e32 v70, 16, v65
	v_and_b32_e32 v71, 0xffff0000, v65
	v_lshlrev_b32_e32 v64, 16, v66
	v_and_b32_e32 v65, 0xffff0000, v66
	v_lshlrev_b32_e32 v66, 16, v67
	v_and_b32_e32 v67, 0xffff0000, v67
.LBB0_269:
	s_andn2_saveexec_b64 s[50:51], s[6:7]
	s_cbranch_execz .LBB0_273
	v_mov_b32_e32 v67, 0
	v_mov_b32_e32 v66, 0
	v_mov_b32_e32 v65, 0
	v_mov_b32_e32 v64, 0
	v_mov_b32_e32 v71, 0
	v_mov_b32_e32 v70, 0
	v_mov_b32_e32 v69, 0
	v_mov_b32_e32 v68, 0
	s_and_saveexec_b64 s[6:7], vcc
	s_cbranch_execz .LBB0_272
	s_load_dwordx2 s[0:1], s[88:89], 0x30
	v_add_u32_e32 v64, 0xffffc000, v76
	v_lshrrev_b32_e32 v64, 2, v64
	v_readlane_b32 s3, v254, 46
	s_nop 1
	v_add_u32_e32 v66, s3, v64
	s_waitcnt lgkmcnt(0)
	v_mov_b64_e32 v[64:65], s[0:1]
	s_movk_i32 s0, 0x1c00
	v_mad_u64_u32 v[64:65], s[0:1], v66, s0, v[64:65]
	v_lshl_add_u64 v[64:65], v[122:123], 2, v[64:65]
	global_load_dwordx4 v[68:71], v[64:65], off
	s_nop 0
	global_load_dwordx4 v[64:67], v[64:65], off offset:16
	s_waitcnt vmcnt(0)

; __device__ __forceinline__ float tanh_f(float x) { return 1.0f - 2.0f * rcpf(1.0f + __expf(2.0f * x)); }
; __device__ __forceinline__ void phase_m1(PP P, int l, LAS unsigned char* lds, const Ids I) {
;     ...
;                     const f32x4 m0 = *(const f32x4*)(mu + col), m1 = *(const f32x4*)(mu + col + 4); float xs[8];
; #pragma unroll
;                     for (int j = 0; j < 4; ++j) { xs[j] = cf[j] + (pf[j] - cf[j]) * m0[j]; xs[4 + j] = cf[4 + j] + (pf[4 + j] - cf[4 + j]) * m1[j]; }
;                     if (col >= 1536 && col < 1600) {
; #pragma unroll
;                         for (int j = 0; j < 8; ++j) xs[j] = tanh_f(xs[j]); }
.LBB0_273:
	s_or_b64 exec, exec, s[50:51]
	v_lshlrev_b32_e32 v86, 16, v74
	v_and_b32_e32 v87, 0xffff0000, v74
	v_lshlrev_b32_e32 v88, 16, v75
	v_and_b32_e32 v89, 0xffff0000, v75
	v_lshlrev_b32_e32 v82, 16, v72
	v_and_b32_e32 v83, 0xffff0000, v72
	v_lshlrev_b32_e32 v84, 16, v73
	v_and_b32_e32 v85, 0xffff0000, v73
	v_pk_add_f32 v[68:69], v[68:69], v[82:83] neg_lo:[0,1] neg_hi:[0,1]
	v_pk_add_f32 v[64:65], v[64:65], v[86:87] neg_lo:[0,1] neg_hi:[0,1]
	v_pk_fma_f32 v[72:73], v[176:177], v[68:69], v[82:83]
	v_pk_fma_f32 v[68:69], v[64:65], v[180:181], v[86:87]
	v_pk_add_f32 v[64:65], v[70:71], v[84:85] neg_lo:[0,1] neg_hi:[0,1]
	s_nop 0
	v_pk_fma_f32 v[74:75], v[178:179], v[64:65], v[84:85]
	v_pk_add_f32 v[64:65], v[66:67], v[88:89] neg_lo:[0,1] neg_hi:[0,1]
	s_nop 0
	v_pk_fma_f32 v[70:71], v[64:65], v[182:183], v[88:89]
	global_load_dwordx4 v[180:183], v[132:133], off offset:16
	global_load_dwordx4 v[176:179], v[132:133], off
	s_and_saveexec_b64 s[50:51], s[24:25]
	s_cbranch_execz .LBB0_275
	v_add_f32_e32 v64, v72, v72
	v_add_f32_e32 v65, v73, v73
	v_add_f32_e32 v66, v74, v74
	v_add_f32_e32 v67, v75, v75
	v_add_f32_e32 v68, v68, v68
	v_add_f32_e32 v69, v69, v69
	v_add_f32_e32 v70, v70, v70
	v_add_f32_e32 v71, v71, v71
	v_mul_f32_e32 v64, 0x3fb8aa3b, v64
	v_mul_f32_e32 v65, 0x3fb8aa3b, v65
	v_mul_f32_e32 v66, 0x3fb8aa3b, v66
	v_mul_f32_e32 v67, 0x3fb8aa3b, v67
	v_mul_f32_e32 v68, 0x3fb8aa3b, v68
	v_mul_f32_e32 v69, 0x3fb8aa3b, v69
	v_mul_f32_e32 v70, 0x3fb8aa3b, v70
	v_mul_f32_e32 v71, 0x3fb8aa3b, v71
	v_exp_f32_e32 v64, v64
	v_exp_f32_e32 v65, v65
	v_exp_f32_e32 v66, v66
	v_exp_f32_e32 v67, v67
	v_exp_f32_e32 v68, v68
	v_exp_f32_e32 v69, v69
	v_exp_f32_e32 v70, v70
	v_exp_f32_e32 v71, v71
	v_add_f32_e32 v64, 1.0, v64
	v_add_f32_e32 v65, 1.0, v65
	v_add_f32_e32 v66, 1.0, v66
	v_add_f32_e32 v67, 1.0, v67
	v_add_f32_e32 v68, 1.0, v68
	v_add_f32_e32 v69, 1.0, v69
	v_add_f32_e32 v70, 1.0, v70
	v_add_f32_e32 v71, 1.0, v71
	v_rcp_f32_e32 v64, v64
	v_rcp_f32_e32 v66, v66
	v_rcp_f32_e32 v68, v68
	v_rcp_f32_e32 v70, v70
	v_rcp_f32_e32 v71, v71
	v_rcp_f32_e32 v69, v69
	v_rcp_f32_e32 v67, v67
	v_rcp_f32_e32 v65, v65
	v_pk_fma_f32 v[70:71], v[70:71], -2.0, 1.0 op_sel_hi:[1,0,0]
	v_pk_fma_f32 v[68:69], v[68:69], -2.0, 1.0 op_sel_hi:[1,0,0]
	v_pk_fma_f32 v[74:75], v[66:67], -2.0, 1.0 op_sel_hi:[1,0,0]
	v_pk_fma_f32 v[72:73], v[64:65], -2.0, 1.0 op_sel_hi:[1,0,0]

; __device__ __forceinline__ void phase_m1(PP P, int l, LAS unsigned char* lds, const Ids I) {
;     ...
;             for (int it = 0; it < 7; ++it) { const int e = tid + 512 * it;
;                 if (e < 16 * 208) { const int tok = e / 208, col = (e - tok * 208) * 8, r = r0 + tok, t = t_in_seq(r);
;                     float cf[8], pf[8]; unpack8(*(const u32x4*)(PR + (size_t)r * INW + 1024 + col), cf);
;                     if (t > 0) unpack8(*(const u32x4*)(PR + (size_t)(r - 1) * INW + 1024 + col), pf);
;                     else if (r < MTP) {
; #pragma unroll
;                         for (int j = 0; j < 8; ++j) pf[j] = 0.f; }
;                     else { const float* sp = P->in[I_SSHIFT] + ((size_t)l * 128 + ((r - MTP) >> 2)) * PW + col; const f32x4 s0 = *(const f32x4*)sp, s1 = *(const f32x4*)(sp + 4);
; #pragma unroll
;                         for (int j = 0; j < 4; ++j) { pf[j] = s0[j]; pf[4 + j] = s1[j]; } }
.LBB0_279:
	s_or_b64 exec, exec, s[68:69]
	s_and_saveexec_b64 s[68:69], s[28:29]
	s_cbranch_execz .LBB0_292
	v_add_u32_e32 v76, s54, v129
	s_waitcnt vmcnt(0)
	v_mov_b32_e32 v72, v242
	v_mov_b32_e32 v73, v243
	v_mov_b32_e32 v74, v244
	v_mov_b32_e32 v75, v245
	v_mov_b32_e32 v64, v246
	v_mov_b32_e32 v65, v247
	v_mov_b32_e32 v66, v248
	v_mov_b32_e32 v67, v249
	v_add_u32_e32 v252, s54, v137
	v_mad_i64_i32 v[250:251], s[0:1], v252, s73, v[170:171]
	global_load_dwordx4 v[242:245], v[250:251], off offset:2048
	v_add_u32_e32 v252, -1, v252
	v_mad_i64_i32 v[250:251], s[0:1], v252, s73, v[170:171]
	global_load_dwordx4 v[246:249], v[250:251], off offset:2048
	v_cmp_gt_i32_e64 s[50:51], s91, v76
	v_cmp_lt_i32_e32 vcc, s76, v76
	s_nop 0
	v_cndmask_b32_e64 v252, 3, v185, s[50:51]
	v_and_b32_e32 v252, v252, v76
	v_cmp_ne_u32_e64 s[50:51], 0, v252
	s_and_saveexec_b64 s[0:1], s[50:51]
	s_xor_b64 s[6:7], exec, s[0:1]
	s_cbranch_execz .LBB0_282
	v_lshlrev_b32_e32 v68, 16, v64
	v_and_b32_e32 v69, 0xffff0000, v64
	v_lshlrev_b32_e32 v70, 16, v65
	v_and_b32_e32 v71, 0xffff0000, v65
	v_lshlrev_b32_e32 v64, 16, v66
	v_and_b32_e32 v65, 0xffff0000, v66
	v_lshlrev_b32_e32 v66, 16, v67
	v_and_b32_e32 v67, 0xffff0000, v67
.LBB0_282:
	s_andn2_saveexec_b64 s[50:51], s[6:7]
	s_cbranch_execz .LBB0_286
	v_mov_b32_e32 v67, 0
	v_mov_b32_e32 v66, 0
	v_mov_b32_e32 v65, 0
	v_mov_b32_e32 v64, 0
	v_mov_b32_e32 v71, 0
	v_mov_b32_e32 v70, 0
	v_mov_b32_e32 v69, 0
	v_mov_b32_e32 v68, 0
	s_and_saveexec_b64 s[6:7], vcc
	s_cbranch_execz .LBB0_285
	s_load_dwordx2 s[0:1], s[88:89], 0x30
	v_add_u32_e32 v64, 0xffffc000, v76
	v_lshrrev_b32_e32 v64, 2, v64
	v_readlane_b32 s3, v254, 46
	s_nop 1
	v_add_u32_e32 v66, s3, v64
	s_waitcnt lgkmcnt(0)
	v_mov_b64_e32 v[64:65], s[0:1]
	s_movk_i32 s0, 0x1c00
	v_mad_u64_u32 v[64:65], s[0:1], v66, s0, v[64:65]
	v_lshl_add_u64 v[64:65], v[130:131], 2, v[64:65]
	global_load_dwordx4 v[68:71], v[64:65], off
	s_nop 0
	global_load_dwordx4 v[64:67], v[64:65], off offset:16
	s_waitcnt vmcnt(0)

; __device__ __forceinline__ float tanh_f(float x) { return 1.0f - 2.0f * rcpf(1.0f + __expf(2.0f * x)); }
; __device__ __forceinline__ void phase_m1(PP P, int l, LAS unsigned char* lds, const Ids I) {
;     ...
;                     const f32x4 m0 = *(const f32x4*)(mu + col), m1 = *(const f32x4*)(mu + col + 4); float xs[8];
; #pragma unroll
;                     for (int j = 0; j < 4; ++j) { xs[j] = cf[j] + (pf[j] - cf[j]) * m0[j]; xs[4 + j] = cf[4 + j] + (pf[4 + j] - cf[4 + j]) * m1[j]; }
;                     if (col >= 1536 && col < 1600) {
; #pragma unroll
;                         for (int j = 0; j < 8; ++j) xs[j] = tanh_f(xs[j]); }
.LBB0_286:
	s_or_b64 exec, exec, s[50:51]
	v_lshlrev_b32_e32 v86, 16, v74
	v_and_b32_e32 v87, 0xffff0000, v74
	v_lshlrev_b32_e32 v88, 16, v75
	v_and_b32_e32 v89, 0xffff0000, v75
	v_lshlrev_b32_e32 v82, 16, v72
	v_and_b32_e32 v83, 0xffff0000, v72
	v_lshlrev_b32_e32 v84, 16, v73
	v_and_b32_e32 v85, 0xffff0000, v73
	v_pk_add_f32 v[68:69], v[68:69], v[82:83] neg_lo:[0,1] neg_hi:[0,1]
	v_pk_add_f32 v[64:65], v[64:65], v[86:87] neg_lo:[0,1] neg_hi:[0,1]
	v_pk_fma_f32 v[72:73], v[176:177], v[68:69], v[82:83]
	v_pk_fma_f32 v[68:69], v[64:65], v[180:181], v[86:87]
	v_pk_add_f32 v[64:65], v[70:71], v[84:85] neg_lo:[0,1] neg_hi:[0,1]
	s_nop 0
	v_pk_fma_f32 v[74:75], v[178:179], v[64:65], v[84:85]
	v_pk_add_f32 v[64:65], v[66:67], v[88:89] neg_lo:[0,1] neg_hi:[0,1]
	s_nop 0
	v_pk_fma_f32 v[70:71], v[64:65], v[182:183], v[88:89]
	global_load_dwordx4 v[180:183], v[140:141], off offset:16
	global_load_dwordx4 v[176:179], v[140:141], off
	s_and_saveexec_b64 s[50:51], s[30:31]
	s_cbranch_execz .LBB0_288
	v_add_f32_e32 v64, v72, v72
	v_add_f32_e32 v65, v73, v73
	v_add_f32_e32 v66, v74, v74
	v_add_f32_e32 v67, v75, v75
	v_add_f32_e32 v68, v68, v68
	v_add_f32_e32 v69, v69, v69
	v_add_f32_e32 v70, v70, v70
	v_add_f32_e32 v71, v71, v71
	v_mul_f32_e32 v64, 0x3fb8aa3b, v64
	v_mul_f32_e32 v65, 0x3fb8aa3b, v65
	v_mul_f32_e32 v66, 0x3fb8aa3b, v66
	v_mul_f32_e32 v67, 0x3fb8aa3b, v67
	v_mul_f32_e32 v68, 0x3fb8aa3b, v68
	v_mul_f32_e32 v69, 0x3fb8aa3b, v69
	v_mul_f32_e32 v70, 0x3fb8aa3b, v70
	v_mul_f32_e32 v71, 0x3fb8aa3b, v71
	v_exp_f32_e32 v64, v64
	v_exp_f32_e32 v65, v65
	v_exp_f32_e32 v66, v66
	v_exp_f32_e32 v67, v67
	v_exp_f32_e32 v68, v68
	v_exp_f32_e32 v69, v69
	v_exp_f32_e32 v70, v70
	v_exp_f32_e32 v71, v71
	v_add_f32_e32 v64, 1.0, v64
	v_add_f32_e32 v65, 1.0, v65
	v_add_f32_e32 v66, 1.0, v66
	v_add_f32_e32 v67, 1.0, v67
	v_add_f32_e32 v68, 1.0, v68
	v_add_f32_e32 v69, 1.0, v69
	v_add_f32_e32 v70, 1.0, v70
	v_add_f32_e32 v71, 1.0, v71
	v_rcp_f32_e32 v64, v64
	v_rcp_f32_e32 v66, v66
	v_rcp_f32_e32 v68, v68
	v_rcp_f32_e32 v70, v70
	v_rcp_f32_e32 v71, v71
	v_rcp_f32_e32 v69, v69
	v_rcp_f32_e32 v67, v67
	v_rcp_f32_e32 v65, v65
	v_pk_fma_f32 v[70:71], v[70:71], -2.0, 1.0 op_sel_hi:[1,0,0]
	v_pk_fma_f32 v[68:69], v[68:69], -2.0, 1.0 op_sel_hi:[1,0,0]
	v_pk_fma_f32 v[74:75], v[66:67], -2.0, 1.0 op_sel_hi:[1,0,0]
	v_pk_fma_f32 v[72:73], v[64:65], -2.0, 1.0 op_sel_hi:[1,0,0]

; __device__ __forceinline__ void phase_m1(PP P, int l, LAS unsigned char* lds, const Ids I) {
;     ...
;             for (int it = 0; it < 7; ++it) { const int e = tid + 512 * it;
;                 if (e < 16 * 208) { const int tok = e / 208, col = (e - tok * 208) * 8, r = r0 + tok, t = t_in_seq(r);
;                     float cf[8], pf[8]; unpack8(*(const u32x4*)(PR + (size_t)r * INW + 1024 + col), cf);
;                     if (t > 0) unpack8(*(const u32x4*)(PR + (size_t)(r - 1) * INW + 1024 + col), pf);
;                     else if (r < MTP) {
; #pragma unroll
;                         for (int j = 0; j < 8; ++j) pf[j] = 0.f; }
;                     else { const float* sp = P->in[I_SSHIFT] + ((size_t)l * 128 + ((r - MTP) >> 2)) * PW + col; const f32x4 s0 = *(const f32x4*)sp, s1 = *(const f32x4*)(sp + 4);
; #pragma unroll
;                         for (int j = 0; j < 4; ++j) { pf[j] = s0[j]; pf[4 + j] = s1[j]; } }
.LBB0_292:
	s_or_b64 exec, exec, s[68:69]
	s_and_saveexec_b64 s[68:69], s[36:37]
	s_cbranch_execz .LBB0_305
	v_add_u32_e32 v76, s54, v137
	s_waitcnt vmcnt(0)
	v_mov_b32_e32 v72, v242
	v_mov_b32_e32 v73, v243
	v_mov_b32_e32 v74, v244
	v_mov_b32_e32 v75, v245
	v_mov_b32_e32 v64, v246
	v_mov_b32_e32 v65, v247
	v_mov_b32_e32 v66, v248
	v_mov_b32_e32 v67, v249
	v_add_u32_e32 v252, s54, v153
	v_mad_i64_i32 v[250:251], s[0:1], v252, s73, v[172:173]
	global_load_dwordx4 v[242:245], v[250:251], off offset:2048
	v_add_u32_e32 v252, -1, v252
	v_mad_i64_i32 v[250:251], s[0:1], v252, s73, v[172:173]
	global_load_dwordx4 v[246:249], v[250:251], off offset:2048
	v_cmp_gt_i32_e64 s[50:51], s91, v76
	v_cmp_lt_i32_e32 vcc, s76, v76
	s_nop 0
	v_cndmask_b32_e64 v252, 3, v185, s[50:51]
	v_and_b32_e32 v252, v252, v76
	v_cmp_ne_u32_e64 s[50:51], 0, v252
	s_and_saveexec_b64 s[0:1], s[50:51]
	s_xor_b64 s[6:7], exec, s[0:1]
	s_cbranch_execz .LBB0_295
	v_lshlrev_b32_e32 v68, 16, v64
	v_and_b32_e32 v69, 0xffff0000, v64
	v_lshlrev_b32_e32 v70, 16, v65
	v_and_b32_e32 v71, 0xffff0000, v65
	v_lshlrev_b32_e32 v64, 16, v66
	v_and_b32_e32 v65, 0xffff0000, v66
	v_lshlrev_b32_e32 v66, 16, v67
	v_and_b32_e32 v67, 0xffff0000, v67
.LBB0_295:
	s_andn2_saveexec_b64 s[50:51], s[6:7]
	s_cbranch_execz .LBB0_299
	v_mov_b32_e32 v67, 0
	v_mov_b32_e32 v66, 0
	v_mov_b32_e32 v65, 0
	v_mov_b32_e32 v64, 0
	v_mov_b32_e32 v71, 0
	v_mov_b32_e32 v70, 0
	v_mov_b32_e32 v69, 0
	v_mov_b32_e32 v68, 0
	s_and_saveexec_b64 s[6:7], vcc
	s_cbranch_execz .LBB0_298
	s_load_dwordx2 s[0:1], s[88:89], 0x30
	v_add_u32_e32 v64, 0xffffc000, v76
	v_lshrrev_b32_e32 v64, 2, v64
	v_readlane_b32 s3, v254, 46
	s_nop 1
	v_add_u32_e32 v66, s3, v64
	s_waitcnt lgkmcnt(0)
	v_mov_b64_e32 v[64:65], s[0:1]
	s_movk_i32 s0, 0x1c00
	v_mad_u64_u32 v[64:65], s[0:1], v66, s0, v[64:65]
	v_lshl_add_u64 v[64:65], v[138:139], 2, v[64:65]
	global_load_dwordx4 v[68:71], v[64:65], off
	s_nop 0
	global_load_dwordx4 v[64:67], v[64:65], off offset:16
	s_waitcnt vmcnt(0)

; __device__ __forceinline__ float tanh_f(float x) { return 1.0f - 2.0f * rcpf(1.0f + __expf(2.0f * x)); }
; __device__ __forceinline__ void phase_m1(PP P, int l, LAS unsigned char* lds, const Ids I) {
;     ...
;                     const f32x4 m0 = *(const f32x4*)(mu + col), m1 = *(const f32x4*)(mu + col + 4); float xs[8];
; #pragma unroll
;                     for (int j = 0; j < 4; ++j) { xs[j] = cf[j] + (pf[j] - cf[j]) * m0[j]; xs[4 + j] = cf[4 + j] + (pf[4 + j] - cf[4 + j]) * m1[j]; }
;                     if (col >= 1536 && col < 1600) {
; #pragma unroll
;                         for (int j = 0; j < 8; ++j) xs[j] = tanh_f(xs[j]); }
.LBB0_299:
	s_or_b64 exec, exec, s[50:51]
	v_lshlrev_b32_e32 v86, 16, v74
	v_and_b32_e32 v87, 0xffff0000, v74
	v_lshlrev_b32_e32 v88, 16, v75
	v_and_b32_e32 v89, 0xffff0000, v75
	v_lshlrev_b32_e32 v82, 16, v72
	v_and_b32_e32 v83, 0xffff0000, v72
	v_lshlrev_b32_e32 v84, 16, v73
	v_and_b32_e32 v85, 0xffff0000, v73
	v_pk_add_f32 v[68:69], v[68:69], v[82:83] neg_lo:[0,1] neg_hi:[0,1]
	v_pk_add_f32 v[64:65], v[64:65], v[86:87] neg_lo:[0,1] neg_hi:[0,1]
	v_pk_fma_f32 v[72:73], v[176:177], v[68:69], v[82:83]
	v_pk_fma_f32 v[68:69], v[64:65], v[180:181], v[86:87]
	v_pk_add_f32 v[64:65], v[70:71], v[84:85] neg_lo:[0,1] neg_hi:[0,1]
	s_nop 0
	v_pk_fma_f32 v[74:75], v[178:179], v[64:65], v[84:85]
	v_pk_add_f32 v[64:65], v[66:67], v[88:89] neg_lo:[0,1] neg_hi:[0,1]
	s_nop 0
	v_pk_fma_f32 v[70:71], v[64:65], v[182:183], v[88:89]
	global_load_dwordx4 v[180:183], v[156:157], off offset:16
	global_load_dwordx4 v[176:179], v[156:157], off
	s_and_saveexec_b64 s[50:51], s[38:39]
	s_cbranch_execz .LBB0_301
	v_add_f32_e32 v64, v72, v72
	v_add_f32_e32 v65, v73, v73
	v_add_f32_e32 v66, v74, v74
	v_add_f32_e32 v67, v75, v75
	v_add_f32_e32 v68, v68, v68
	v_add_f32_e32 v69, v69, v69
	v_add_f32_e32 v70, v70, v70
	v_add_f32_e32 v71, v71, v71
	v_mul_f32_e32 v64, 0x3fb8aa3b, v64
	v_mul_f32_e32 v65, 0x3fb8aa3b, v65
	v_mul_f32_e32 v66, 0x3fb8aa3b, v66
	v_mul_f32_e32 v67, 0x3fb8aa3b, v67
	v_mul_f32_e32 v68, 0x3fb8aa3b, v68
	v_mul_f32_e32 v69, 0x3fb8aa3b, v69
	v_mul_f32_e32 v70, 0x3fb8aa3b, v70
	v_mul_f32_e32 v71, 0x3fb8aa3b, v71
	v_exp_f32_e32 v64, v64
	v_exp_f32_e32 v65, v65
	v_exp_f32_e32 v66, v66
	v_exp_f32_e32 v67, v67
	v_exp_f32_e32 v68, v68
	v_exp_f32_e32 v69, v69
	v_exp_f32_e32 v70, v70
	v_exp_f32_e32 v71, v71
	v_add_f32_e32 v64, 1.0, v64
	v_add_f32_e32 v65, 1.0, v65
	v_add_f32_e32 v66, 1.0, v66
	v_add_f32_e32 v67, 1.0, v67
	v_add_f32_e32 v68, 1.0, v68
	v_add_f32_e32 v69, 1.0, v69
	v_add_f32_e32 v70, 1.0, v70
	v_add_f32_e32 v71, 1.0, v71
	v_rcp_f32_e32 v64, v64
	v_rcp_f32_e32 v66, v66
	v_rcp_f32_e32 v68, v68
	v_rcp_f32_e32 v70, v70
	v_rcp_f32_e32 v71, v71
	v_rcp_f32_e32 v69, v69
	v_rcp_f32_e32 v67, v67
	v_rcp_f32_e32 v65, v65
	v_pk_fma_f32 v[70:71], v[70:71], -2.0, 1.0 op_sel_hi:[1,0,0]
	v_pk_fma_f32 v[68:69], v[68:69], -2.0, 1.0 op_sel_hi:[1,0,0]
	v_pk_fma_f32 v[74:75], v[66:67], -2.0, 1.0 op_sel_hi:[1,0,0]
	v_pk_fma_f32 v[72:73], v[64:65], -2.0, 1.0 op_sel_hi:[1,0,0]

; __device__ __forceinline__ void phase_m1(PP P, int l, LAS unsigned char* lds, const Ids I) {
;     ...
;             for (int it = 0; it < 7; ++it) { const int e = tid + 512 * it;
;                 if (e < 16 * 208) { const int tok = e / 208, col = (e - tok * 208) * 8, r = r0 + tok, t = t_in_seq(r);
;                     float cf[8], pf[8]; unpack8(*(const u32x4*)(PR + (size_t)r * INW + 1024 + col), cf);
;                     if (t > 0) unpack8(*(const u32x4*)(PR + (size_t)(r - 1) * INW + 1024 + col), pf);
;                     else if (r < MTP) {
; #pragma unroll
;                         for (int j = 0; j < 8; ++j) pf[j] = 0.f; }
;                     else { const float* sp = P->in[I_SSHIFT] + ((size_t)l * 128 + ((r - MTP) >> 2)) * PW + col; const f32x4 s0 = *(const f32x4*)sp, s1 = *(const f32x4*)(sp + 4);
; #pragma unroll
;                         for (int j = 0; j < 4; ++j) { pf[j] = s0[j]; pf[4 + j] = s1[j]; } }
.LBB0_305:
	s_or_b64 exec, exec, s[68:69]
	s_and_saveexec_b64 s[68:69], s[42:43]
	s_cbranch_execz .LBB0_226
	v_add_u32_e32 v76, s54, v153
	s_waitcnt vmcnt(0)
	v_mov_b32_e32 v72, v242
	v_mov_b32_e32 v73, v243
	v_mov_b32_e32 v74, v244
	v_mov_b32_e32 v75, v245
	v_mov_b32_e32 v64, v246
	v_mov_b32_e32 v65, v247
	v_mov_b32_e32 v66, v248
	v_mov_b32_e32 v67, v249
	v_cmp_gt_i32_e64 s[50:51], s91, v76
	v_cmp_lt_i32_e32 vcc, s76, v76
	s_nop 0
	v_cndmask_b32_e64 v252, 3, v185, s[50:51]
	v_and_b32_e32 v252, v252, v76
	v_cmp_ne_u32_e64 s[50:51], 0, v252
	s_and_saveexec_b64 s[0:1], s[50:51]
	s_xor_b64 s[6:7], exec, s[0:1]
	s_cbranch_execz .LBB0_308
	v_lshlrev_b32_e32 v68, 16, v64
	v_and_b32_e32 v69, 0xffff0000, v64
	v_lshlrev_b32_e32 v70, 16, v65
	v_and_b32_e32 v71, 0xffff0000, v65
	v_lshlrev_b32_e32 v64, 16, v66
	v_and_b32_e32 v65, 0xffff0000, v66
	v_lshlrev_b32_e32 v66, 16, v67
	v_and_b32_e32 v67, 0xffff0000, v67
.LBB0_308:
	s_andn2_saveexec_b64 s[50:51], s[6:7]
	s_cbranch_execz .LBB0_312
	v_mov_b32_e32 v67, 0
	v_mov_b32_e32 v66, 0
	v_mov_b32_e32 v65, 0
	v_mov_b32_e32 v64, 0
	v_mov_b32_e32 v71, 0
	v_mov_b32_e32 v70, 0
	v_mov_b32_e32 v69, 0
	v_mov_b32_e32 v68, 0
	s_and_saveexec_b64 s[6:7], vcc
	s_cbranch_execz .LBB0_311
	s_load_dwordx2 s[0:1], s[88:89], 0x30
	v_add_u32_e32 v64, 0xffffc000, v76
	v_lshrrev_b32_e32 v64, 2, v64
	v_readlane_b32 s3, v254, 46
	s_nop 1
	v_add_u32_e32 v66, s3, v64
	s_waitcnt lgkmcnt(0)
	v_mov_b64_e32 v[64:65], s[0:1]
	s_movk_i32 s0, 0x1c00
	v_mad_u64_u32 v[64:65], s[0:1], v66, s0, v[64:65]
	v_lshl_add_u64 v[64:65], v[154:155], 2, v[64:65]
	global_load_dwordx4 v[68:71], v[64:65], off
	s_nop 0
	global_load_dwordx4 v[64:67], v[64:65], off offset:16
	s_waitcnt vmcnt(0)

; __device__ __forceinline__ float tanh_f(float x) { return 1.0f - 2.0f * rcpf(1.0f + __expf(2.0f * x)); }
; __device__ __forceinline__ void phase_m1(PP P, int l, LAS unsigned char* lds, const Ids I) {
;     ...
;                     const f32x4 m0 = *(const f32x4*)(mu + col), m1 = *(const f32x4*)(mu + col + 4); float xs[8];
; #pragma unroll
;                     for (int j = 0; j < 4; ++j) { xs[j] = cf[j] + (pf[j] - cf[j]) * m0[j]; xs[4 + j] = cf[4 + j] + (pf[4 + j] - cf[4 + j]) * m1[j]; }
;                     if (col >= 1536 && col < 1600) {
; #pragma unroll
;                         for (int j = 0; j < 8; ++j) xs[j] = tanh_f(xs[j]); }
.LBB0_312:
	s_or_b64 exec, exec, s[50:51]
	v_lshlrev_b32_e32 v86, 16, v74
	v_and_b32_e32 v87, 0xffff0000, v74
	v_lshlrev_b32_e32 v88, 16, v75
	v_and_b32_e32 v89, 0xffff0000, v75
	v_lshlrev_b32_e32 v82, 16, v72
	v_and_b32_e32 v83, 0xffff0000, v72
	v_lshlrev_b32_e32 v84, 16, v73
	v_and_b32_e32 v85, 0xffff0000, v73
	v_pk_add_f32 v[68:69], v[68:69], v[82:83] neg_lo:[0,1] neg_hi:[0,1]
	v_pk_add_f32 v[64:65], v[64:65], v[86:87] neg_lo:[0,1] neg_hi:[0,1]
	v_pk_fma_f32 v[72:73], v[176:177], v[68:69], v[82:83]
	v_pk_fma_f32 v[68:69], v[64:65], v[180:181], v[86:87]
	v_pk_add_f32 v[64:65], v[70:71], v[84:85] neg_lo:[0,1] neg_hi:[0,1]
	s_nop 0
	v_pk_fma_f32 v[74:75], v[178:179], v[64:65], v[84:85]
	v_pk_add_f32 v[64:65], v[66:67], v[88:89] neg_lo:[0,1] neg_hi:[0,1]
	s_nop 0
	v_pk_fma_f32 v[70:71], v[64:65], v[182:183], v[88:89]
	s_and_saveexec_b64 s[50:51], s[44:45]
	s_cbranch_execz .LBB0_314
	v_add_f32_e32 v64, v72, v72
	v_add_f32_e32 v65, v73, v73
	v_add_f32_e32 v66, v74, v74
	v_add_f32_e32 v67, v75, v75
	v_add_f32_e32 v68, v68, v68
	v_add_f32_e32 v69, v69, v69
	v_add_f32_e32 v70, v70, v70
	v_add_f32_e32 v71, v71, v71
	v_mul_f32_e32 v64, 0x3fb8aa3b, v64
	v_mul_f32_e32 v65, 0x3fb8aa3b, v65
	v_mul_f32_e32 v66, 0x3fb8aa3b, v66
	v_mul_f32_e32 v67, 0x3fb8aa3b, v67
	v_mul_f32_e32 v68, 0x3fb8aa3b, v68
	v_mul_f32_e32 v69, 0x3fb8aa3b, v69
	v_mul_f32_e32 v70, 0x3fb8aa3b, v70
	v_mul_f32_e32 v71, 0x3fb8aa3b, v71
	v_exp_f32_e32 v64, v64
	v_exp_f32_e32 v65, v65
	v_exp_f32_e32 v66, v66
	v_exp_f32_e32 v67, v67
	v_exp_f32_e32 v68, v68
	v_exp_f32_e32 v69, v69
	v_exp_f32_e32 v70, v70
	v_exp_f32_e32 v71, v71
	v_add_f32_e32 v64, 1.0, v64
	v_add_f32_e32 v65, 1.0, v65
	v_add_f32_e32 v66, 1.0, v66
	v_add_f32_e32 v67, 1.0, v67
	v_add_f32_e32 v68, 1.0, v68
	v_add_f32_e32 v69, 1.0, v69
	v_add_f32_e32 v70, 1.0, v70
	v_add_f32_e32 v71, 1.0, v71
	v_rcp_f32_e32 v64, v64
	v_rcp_f32_e32 v66, v66
	v_rcp_f32_e32 v68, v68
	v_rcp_f32_e32 v70, v70
	v_rcp_f32_e32 v71, v71
	v_rcp_f32_e32 v69, v69
	v_rcp_f32_e32 v67, v67
	v_rcp_f32_e32 v65, v65
	v_pk_fma_f32 v[70:71], v[70:71], -2.0, 1.0 op_sel_hi:[1,0,0]
	v_pk_fma_f32 v[68:69], v[68:69], -2.0, 1.0 op_sel_hi:[1,0,0]
	v_pk_fma_f32 v[74:75], v[66:67], -2.0, 1.0 op_sel_hi:[1,0,0]
	v_pk_fma_f32 v[72:73], v[64:65], -2.0, 1.0 op_sel_hi:[1,0,0]
